# modnorm loops in block form: 4 consecutive rows per block, scale/shift vectors loaded once per block, DPP row-sum reduction (P8, P11, P18)
# speedup vs baseline: 1.0096x; 1.0014x over previous
; __device__ __forceinline__ unsigned cvt_pk_bf16(float lo, float hi) { unsigned r; asm volatile("v_cvt_pk_bf16_f32 %0, %1, %2" : "=v"(r) : "v"(lo), "v"(hi)); return r; }
; #define LANE_IDS() const int f_tid = tid_(); const int f_lane = f_tid & 63; const int f_gtid = blockIdx.x * (NWAVES * 64) + f_tid; (void)f_lane; (void)f_gtid
;     LANE_IDS();
;     if (F.gw >= wave0) for (int row = row_begin + (F.gw - wave0); row < nrows; row += F.NGW - wave0) {
;         const bool isctx = row >= NLAT; const int b = isctx ? 8 : (row >> 12);
;         const size_t roff = isctx ? (size_t)(row - NLAT) * DM : (size_t)row * DM; const void* sp = isctx ? src_ctx : src_lat;
;         f32x4 v[4]; float ss = 0.f;
;         if (SB) { const u32x2* xr = (const u32x2*)((const bf16*)sp + roff) + f_lane;
; #pragma unroll
;             for (int j = 0; j < 4; ++j) { const u32x2 r = xr[64 * j]; v[j] = (f32x4){__uint_as_float(r.x << 16), __uint_as_float(r.x & 0xffff0000u), __uint_as_float(r.y << 16), __uint_as_float(r.y & 0xffff0000u)}; } }
;         else { const f32x4* xr = (const f32x4*)((const float*)sp + roff) + f_lane;
; #pragma unroll
;             for (int j = 0; j < 4; ++j) v[j] = xr[64 * j]; }
;         if (part != nullptr && isctx) {
;             const f32x4* p0 = (const f32x4*)(part + (size_t)(row - NLAT) * DM) + f_lane; const f32x4* p1 = p0 + (size_t)NCTX * DM / 4; const f32x4* g4p = (const f32x4*)pgate + f_lane;
; #pragma unroll
;             for (int j = 0; j < 4; ++j) v[j] += g4p[64 * j] * (p0[64 * j] + p1[64 * j]); }
; #pragma unroll
;         for (int j = 0; j < 4; ++j) ss += (v[j].x * v[j].x + v[j].y * v[j].y) + (v[j].z * v[j].z + v[j].w * v[j].w);
;         const float rstd = rsqrtf(wave_sum(ss) * (1.0f / DM) + EPS);
;         const f32x4* g4 = (const f32x4*)gnorm + f_lane; const f32x4* sh4 = (const f32x4*)(modl + b * MODS + shc * DM) + f_lane; const f32x4* sc4 = (const f32x4*)(modl + b * MODS + scc * DM) + f_lane;
;         u32x2* o8 = (u32x2*)(H + (size_t)row * DM) + f_lane;
; #pragma unroll
;         for (int j = 0; j < 4; ++j) { const f32x4 y = v[j] * rstd * g4[64 * j] * (sc4[64 * j] + 1.0f) + sh4[64 * j];
;             u32x2 w; w.x = cvt_pk_bf16(y.x, y.y); w.y = cvt_pk_bf16(y.z, y.w); o8[64 * j] = w; }
.LBB0_769:
	s_add_u32 s3, s54, 0x1000
	s_addc_u32 s33, s55, 0
	s_mov_b64 s[26:27], s[86:87]
	s_add_u32 s86, s54, 0xe800000
	s_mov_b64 s[22:23], s[80:81]
	s_addc_u32 s87, s55, 0
	s_andn2_b64 vcc, exec, s[4:5]
	s_cbranch_vccnz .LBB0_773
	s_lshl_b32 s12, s84, 3
	s_cmp_lt_i32 s46, s12
	s_cselect_b64 s[8:9], -1, 0
	s_sub_i32 s4, s46, s12
	s_cmpk_gt_i32 s4, 0x7fff
	s_cselect_b64 s[10:11], -1, 0
	s_or_b64 s[8:9], s[8:9], s[10:11]
	s_mov_b64 s[6:7], s[0:1]
	v_mov_b32_e32 v0, v188
	s_and_b64 vcc, exec, s[8:9]
	s_cbranch_vccnz .LBB0_773
	v_and_b32_e32 v16, 63, v0
	v_mbcnt_lo_u32_b32 v0, -1, 0
	v_mbcnt_hi_u32_b32 v0, -1, v0
	v_and_b32_e32 v2, 64, v0
	v_add_u32_e32 v2, 64, v2
	v_xor_b32_e32 v3, 1, v0
	v_cmp_lt_i32_e32 vcc, v3, v2
	s_load_dwordx2 s[6:7], s[6:7], 0x38
	v_mov_b32_e32 v1, 0
	v_cndmask_b32_e32 v3, v0, v3, vcc
	v_lshlrev_b32_e32 v8, 2, v3
	v_xor_b32_e32 v3, 2, v0
	v_cmp_lt_i32_e32 vcc, v3, v2
	v_mov_b32_e32 v14, 0x358637bd
	s_mov_b32 s13, 0x800000
	v_cndmask_b32_e32 v3, v0, v3, vcc
	v_lshlrev_b32_e32 v9, 2, v3
	v_xor_b32_e32 v3, 4, v0
	v_cmp_lt_i32_e32 vcc, v3, v2
	s_mov_b64 s[8:9], 0x4000
	s_movk_i32 s14, 0x4000
	v_cndmask_b32_e32 v3, v0, v3, vcc
	v_lshlrev_b32_e32 v10, 2, v3
	v_xor_b32_e32 v3, 8, v0
	v_cmp_lt_i32_e32 vcc, v3, v2
	s_movk_i32 s15, 0x3000
	v_readlane_b32 s18, v251, 5
	v_cndmask_b32_e32 v3, v0, v3, vcc
	v_lshlrev_b32_e32 v11, 2, v3
	v_xor_b32_e32 v3, 16, v0
	v_cmp_lt_i32_e32 vcc, v3, v2
	v_readlane_b32 s19, v251, 6
	s_nop 0
	v_cndmask_b32_e32 v3, v0, v3, vcc
	v_lshlrev_b32_e32 v12, 2, v3
	v_xor_b32_e32 v3, 32, v0
	v_cmp_lt_i32_e32 vcc, v3, v2
	s_nop 1
	v_cndmask_b32_e32 v0, v0, v3, vcc
	v_lshlrev_b32_e32 v13, 2, v0
	v_lshlrev_b32_e32 v0, 4, v16
	s_waitcnt lgkmcnt(0)
	v_lshl_add_u64 v[2:3], s[6:7], 0, v[0:1]
	v_lshlrev_b32_e32 v0, 3, v16
	v_lshl_add_u64 v[4:5], s[86:87], 0, v[0:1]
	v_lshl_add_u64 v[6:7], s[52:53], 0, v[0:1]
	v_lshlrev_b32_e32 v0, 4, v16
	s_mov_b64 s[6:7], 0x3000
	s_sub_i32 s5, s18, s12
	global_load_dwordx4 v[64:67], v[2:3], off offset:0
	global_load_dwordx4 v[68:71], v[2:3], off offset:1024
	global_load_dwordx4 v[72:75], v[2:3], off offset:2048
	global_load_dwordx4 v[76:79], v[2:3], off offset:3072
	s_mov_b32 s10, s4
	s_lshl_b32 s11, s10, 2
	s_cmp_lt_i32 s11, 0x8000
	s_cbranch_scc0 .Lmn4_p8_done
.Lmn4_p8_blk:
	s_ashr_i32 s100, s10, 10
	s_mul_i32 s100, s100, 0x6000
	s_add_u32 s100, s3, s100
	s_addc_u32 s101, s33, 0
	s_add_u32 s16, s100, 0x4000
	s_addc_u32 s17, s101, 0
	v_lshl_add_u64 v[136:137], s[16:17], 0, v[0:1]
	global_load_dwordx4 v[104:107], v[136:137], off offset:0
	global_load_dwordx4 v[108:111], v[136:137], off offset:1024
	global_load_dwordx4 v[112:115], v[136:137], off offset:2048
	global_load_dwordx4 v[116:119], v[136:137], off offset:3072
	s_add_u32 s16, s100, 0x3000
	s_addc_u32 s17, s101, 0
	v_lshl_add_u64 v[138:139], s[16:17], 0, v[0:1]
	global_load_dwordx4 v[120:123], v[138:139], off offset:0
	global_load_dwordx4 v[124:127], v[138:139], off offset:1024
	global_load_dwordx4 v[128:131], v[138:139], off offset:2048
	global_load_dwordx4 v[132:135], v[138:139], off offset:3072
	s_lshl_b32 s100, s10, 13
	s_mov_b32 s101, 0
	v_lshl_add_u64 v[164:165], v[6:7], 0, s[100:101]
	global_load_dwordx2 v[80:81], v[164:165], off offset:0
	global_load_dwordx2 v[82:83], v[164:165], off offset:512
	global_load_dwordx2 v[84:85], v[164:165], off offset:1024
	global_load_dwordx2 v[86:87], v[164:165], off offset:1536
	s_lshl_b32 s100, s10, 13
	s_add_u32 s100, s100, 0x800
	s_mov_b32 s101, 0
	v_lshl_add_u64 v[164:165], v[6:7], 0, s[100:101]
	global_load_dwordx2 v[88:89], v[164:165], off offset:0
	global_load_dwordx2 v[90:91], v[164:165], off offset:512
	global_load_dwordx2 v[92:93], v[164:165], off offset:1024
	global_load_dwordx2 v[94:95], v[164:165], off offset:1536
	s_lshl_b32 s100, s10, 13
	s_add_u32 s100, s100, 0x1000
	s_mov_b32 s101, 0
	v_lshl_add_u64 v[164:165], v[6:7], 0, s[100:101]
	global_load_dwordx2 v[96:97], v[164:165], off offset:0
	global_load_dwordx2 v[98:99], v[164:165], off offset:512
	global_load_dwordx2 v[100:101], v[164:165], off offset:1024
	global_load_dwordx2 v[102:103], v[164:165], off offset:1536
	s_lshl_b32 s100, s10, 13
	s_add_u32 s100, s100, 0x1800
	s_mov_b32 s101, 0
	v_lshl_add_u64 v[164:165], v[6:7], 0, s[100:101]
	global_load_dwordx2 v[156:157], v[164:165], off offset:0
	global_load_dwordx2 v[158:159], v[164:165], off offset:512
	global_load_dwordx2 v[160:161], v[164:165], off offset:1024
	global_load_dwordx2 v[162:163], v[164:165], off offset:1536
	s_waitcnt vmcnt(0)
;     ...
;         for (int j = 0; j < 4; ++j) ss += (v[j].x * v[j].x + v[j].y * v[j].y) + (v[j].z * v[j].z + v[j].w * v[j].w);
;         const float rstd = rsqrtf(wave_sum(ss) * (1.0f / DM) + EPS);
;         const f32x4* g4 = (const f32x4*)gnorm + f_lane; const f32x4* sh4 = (const f32x4*)(modl + b * MODS + shc * DM) + f_lane; const f32x4* sc4 = (const f32x4*)(modl + b * MODS + scc * DM) + f_lane;
;         u32x2* o8 = (u32x2*)(H + (size_t)row * DM) + f_lane;
; #pragma unroll
;         for (int j = 0; j < 4; ++j) { const f32x4 y = v[j] * rstd * g4[64 * j] * (sc4[64 * j] + 1.0f) + sh4[64 * j];
	v_add_f32_e32 v104, 1.0, v104
	v_add_f32_e32 v105, 1.0, v105
	v_add_f32_e32 v106, 1.0, v106
	v_add_f32_e32 v107, 1.0, v107
	v_add_f32_e32 v108, 1.0, v108
	v_add_f32_e32 v109, 1.0, v109
	v_add_f32_e32 v110, 1.0, v110
	v_add_f32_e32 v111, 1.0, v111
	v_add_f32_e32 v112, 1.0, v112
	v_add_f32_e32 v113, 1.0, v113
	v_add_f32_e32 v114, 1.0, v114
	v_add_f32_e32 v115, 1.0, v115
	v_add_f32_e32 v116, 1.0, v116
	v_add_f32_e32 v117, 1.0, v117
	v_add_f32_e32 v118, 1.0, v118
	v_add_f32_e32 v119, 1.0, v119
	v_lshlrev_b32_e32 v136, 16, v80
	v_and_b32_e32 v137, 0xffff0000, v80
	v_lshlrev_b32_e32 v138, 16, v81
	v_and_b32_e32 v139, 0xffff0000, v81
	v_lshlrev_b32_e32 v140, 16, v82
	v_and_b32_e32 v141, 0xffff0000, v82
	v_lshlrev_b32_e32 v142, 16, v83
	v_and_b32_e32 v143, 0xffff0000, v83
	v_lshlrev_b32_e32 v144, 16, v84
	v_and_b32_e32 v145, 0xffff0000, v84
	v_lshlrev_b32_e32 v146, 16, v85
	v_and_b32_e32 v147, 0xffff0000, v85
	v_lshlrev_b32_e32 v148, 16, v86
	v_and_b32_e32 v149, 0xffff0000, v86
	v_lshlrev_b32_e32 v150, 16, v87
	v_and_b32_e32 v151, 0xffff0000, v87
	v_mul_f32_e32 v28, v136, v136
	v_mul_f32_e32 v32, v137, v137
	v_fmac_f32_e32 v28, v138, v138
	v_fmac_f32_e32 v32, v139, v139
	v_fmac_f32_e32 v28, v140, v140
	v_fmac_f32_e32 v32, v141, v141
	v_fmac_f32_e32 v28, v142, v142
	v_fmac_f32_e32 v32, v143, v143
	v_fmac_f32_e32 v28, v144, v144
	v_fmac_f32_e32 v32, v145, v145
	v_fmac_f32_e32 v28, v146, v146
	v_fmac_f32_e32 v32, v147, v147
	v_fmac_f32_e32 v28, v148, v148
	v_fmac_f32_e32 v32, v149, v149
	v_fmac_f32_e32 v28, v150, v150
	v_fmac_f32_e32 v32, v151, v151
	v_add_f32_e32 v28, v28, v32
	v_lshlrev_b32_e32 v136, 16, v88
	v_and_b32_e32 v137, 0xffff0000, v88
	v_lshlrev_b32_e32 v138, 16, v89
	v_and_b32_e32 v139, 0xffff0000, v89
	v_lshlrev_b32_e32 v140, 16, v90
	v_and_b32_e32 v141, 0xffff0000, v90
	v_lshlrev_b32_e32 v142, 16, v91
	v_and_b32_e32 v143, 0xffff0000, v91
	v_lshlrev_b32_e32 v144, 16, v92
	v_and_b32_e32 v145, 0xffff0000, v92
	v_lshlrev_b32_e32 v146, 16, v93
	v_and_b32_e32 v147, 0xffff0000, v93
	v_lshlrev_b32_e32 v148, 16, v94
	v_and_b32_e32 v149, 0xffff0000, v94
	v_lshlrev_b32_e32 v150, 16, v95
	v_and_b32_e32 v151, 0xffff0000, v95
	v_mul_f32_e32 v29, v136, v136
	v_mul_f32_e32 v32, v137, v137
	v_fmac_f32_e32 v29, v138, v138
	v_fmac_f32_e32 v32, v139, v139
	v_fmac_f32_e32 v29, v140, v140
	v_fmac_f32_e32 v32, v141, v141
	v_fmac_f32_e32 v29, v142, v142
	v_fmac_f32_e32 v32, v143, v143
	v_fmac_f32_e32 v29, v144, v144
	v_fmac_f32_e32 v32, v145, v145
	v_fmac_f32_e32 v29, v146, v146
	v_fmac_f32_e32 v32, v147, v147
	v_fmac_f32_e32 v29, v148, v148
	v_fmac_f32_e32 v32, v149, v149
	v_fmac_f32_e32 v29, v150, v150
	v_fmac_f32_e32 v32, v151, v151
	v_add_f32_e32 v29, v29, v32
	v_lshlrev_b32_e32 v136, 16, v96
	v_and_b32_e32 v137, 0xffff0000, v96
	v_lshlrev_b32_e32 v138, 16, v97
	v_and_b32_e32 v139, 0xffff0000, v97
	v_lshlrev_b32_e32 v140, 16, v98
	v_and_b32_e32 v141, 0xffff0000, v98
	v_lshlrev_b32_e32 v142, 16, v99
	v_and_b32_e32 v143, 0xffff0000, v99
	v_lshlrev_b32_e32 v144, 16, v100
	v_and_b32_e32 v145, 0xffff0000, v100
	v_lshlrev_b32_e32 v146, 16, v101
	v_and_b32_e32 v147, 0xffff0000, v101
	v_lshlrev_b32_e32 v148, 16, v102
	v_and_b32_e32 v149, 0xffff0000, v102
	v_lshlrev_b32_e32 v150, 16, v103
	v_and_b32_e32 v151, 0xffff0000, v103
	v_mul_f32_e32 v30, v136, v136
	v_mul_f32_e32 v32, v137, v137
	v_fmac_f32_e32 v30, v138, v138
	v_fmac_f32_e32 v32, v139, v139
	v_fmac_f32_e32 v30, v140, v140
	v_fmac_f32_e32 v32, v141, v141
	v_fmac_f32_e32 v30, v142, v142
	v_fmac_f32_e32 v32, v143, v143
	v_fmac_f32_e32 v30, v144, v144
	v_fmac_f32_e32 v32, v145, v145
	v_fmac_f32_e32 v30, v146, v146
	v_fmac_f32_e32 v32, v147, v147
	v_fmac_f32_e32 v30, v148, v148
	v_fmac_f32_e32 v32, v149, v149
	v_fmac_f32_e32 v30, v150, v150
	v_fmac_f32_e32 v32, v151, v151
	v_add_f32_e32 v30, v30, v32
	v_lshlrev_b32_e32 v136, 16, v156
	v_and_b32_e32 v137, 0xffff0000, v156
	v_lshlrev_b32_e32 v138, 16, v157
	v_and_b32_e32 v139, 0xffff0000, v157
	v_lshlrev_b32_e32 v140, 16, v158
	v_and_b32_e32 v141, 0xffff0000, v158
	v_lshlrev_b32_e32 v142, 16, v159
	v_and_b32_e32 v143, 0xffff0000, v159
	v_lshlrev_b32_e32 v144, 16, v160
	v_and_b32_e32 v145, 0xffff0000, v160
	v_lshlrev_b32_e32 v146, 16, v161
	v_and_b32_e32 v147, 0xffff0000, v161
	v_lshlrev_b32_e32 v148, 16, v162
	v_and_b32_e32 v149, 0xffff0000, v162
	v_lshlrev_b32_e32 v150, 16, v163
	v_and_b32_e32 v151, 0xffff0000, v163
	v_mul_f32_e32 v31, v136, v136
	v_mul_f32_e32 v32, v137, v137
	v_fmac_f32_e32 v31, v138, v138
	v_fmac_f32_e32 v32, v139, v139
	v_fmac_f32_e32 v31, v140, v140
	v_fmac_f32_e32 v32, v141, v141
	v_fmac_f32_e32 v31, v142, v142
	v_fmac_f32_e32 v32, v143, v143
	v_fmac_f32_e32 v31, v144, v144
	v_fmac_f32_e32 v32, v145, v145
	v_fmac_f32_e32 v31, v146, v146
	v_fmac_f32_e32 v32, v147, v147
	v_fmac_f32_e32 v31, v148, v148
	v_fmac_f32_e32 v32, v149, v149
	v_fmac_f32_e32 v31, v150, v150
	v_fmac_f32_e32 v32, v151, v151
	v_add_f32_e32 v31, v31, v32
	v_add_f32_dpp v28, v28, v28 row_shr:1 row_mask:0xf bank_mask:0xf bound_ctrl:0
	v_add_f32_dpp v29, v29, v29 row_shr:1 row_mask:0xf bank_mask:0xf bound_ctrl:0
	v_add_f32_dpp v30, v30, v30 row_shr:1 row_mask:0xf bank_mask:0xf bound_ctrl:0
	v_add_f32_dpp v31, v31, v31 row_shr:1 row_mask:0xf bank_mask:0xf bound_ctrl:0
	v_add_f32_dpp v28, v28, v28 row_shr:2 row_mask:0xf bank_mask:0xf bound_ctrl:0
	v_add_f32_dpp v29, v29, v29 row_shr:2 row_mask:0xf bank_mask:0xf bound_ctrl:0
	v_add_f32_dpp v30, v30, v30 row_shr:2 row_mask:0xf bank_mask:0xf bound_ctrl:0
	v_add_f32_dpp v31, v31, v31 row_shr:2 row_mask:0xf bank_mask:0xf bound_ctrl:0
	v_add_f32_dpp v28, v28, v28 row_shr:4 row_mask:0xf bank_mask:0xf bound_ctrl:0
; __device__ __forceinline__ unsigned cvt_pk_bf16(float lo, float hi) { unsigned r; asm volatile("v_cvt_pk_bf16_f32 %0, %1, %2" : "=v"(r) : "v"(lo), "v"(hi)); return r; }
;     ...
;         const float rstd = rsqrtf(wave_sum(ss) * (1.0f / DM) + EPS);
;         const f32x4* g4 = (const f32x4*)gnorm + f_lane; const f32x4* sh4 = (const f32x4*)(modl + b * MODS + shc * DM) + f_lane; const f32x4* sc4 = (const f32x4*)(modl + b * MODS + scc * DM) + f_lane;
;         u32x2* o8 = (u32x2*)(H + (size_t)row * DM) + f_lane;
; #pragma unroll
;         for (int j = 0; j < 4; ++j) { const f32x4 y = v[j] * rstd * g4[64 * j] * (sc4[64 * j] + 1.0f) + sh4[64 * j];
;             u32x2 w; w.x = cvt_pk_bf16(y.x, y.y); w.y = cvt_pk_bf16(y.z, y.w); o8[64 * j] = w; }
	v_add_f32_dpp v29, v29, v29 row_shr:4 row_mask:0xf bank_mask:0xf bound_ctrl:0
	v_add_f32_dpp v30, v30, v30 row_shr:4 row_mask:0xf bank_mask:0xf bound_ctrl:0
	v_add_f32_dpp v31, v31, v31 row_shr:4 row_mask:0xf bank_mask:0xf bound_ctrl:0
	v_add_f32_dpp v28, v28, v28 row_shr:8 row_mask:0xf bank_mask:0xf bound_ctrl:0
	v_add_f32_dpp v29, v29, v29 row_shr:8 row_mask:0xf bank_mask:0xf bound_ctrl:0
	v_add_f32_dpp v30, v30, v30 row_shr:8 row_mask:0xf bank_mask:0xf bound_ctrl:0
	v_add_f32_dpp v31, v31, v31 row_shr:8 row_mask:0xf bank_mask:0xf bound_ctrl:0
	v_add_f32_dpp v28, v28, v28 row_bcast:15 row_mask:0xa bank_mask:0xf
	v_add_f32_dpp v29, v29, v29 row_bcast:15 row_mask:0xa bank_mask:0xf
	v_add_f32_dpp v30, v30, v30 row_bcast:15 row_mask:0xa bank_mask:0xf
	v_add_f32_dpp v31, v31, v31 row_bcast:15 row_mask:0xa bank_mask:0xf
	v_add_f32_dpp v28, v28, v28 row_bcast:31 row_mask:0xc bank_mask:0xf
	v_add_f32_dpp v29, v29, v29 row_bcast:31 row_mask:0xc bank_mask:0xf
	v_add_f32_dpp v30, v30, v30 row_bcast:31 row_mask:0xc bank_mask:0xf
	v_add_f32_dpp v31, v31, v31 row_bcast:31 row_mask:0xc bank_mask:0xf
	s_nop 0
	v_readlane_b32 s16, v28, 63
	v_readlane_b32 s17, v29, 63
	v_readlane_b32 vcc_lo, v30, 63
	v_readlane_b32 vcc_hi, v31, 63
	v_mov_b32_e32 v34, s16
	v_fmamk_f32 v34, v34, 0x3a800000, v14
	v_rsq_f32_e32 v33, v34
	v_lshlrev_b32_e32 v136, 16, v80
	v_and_b32_e32 v137, 0xffff0000, v80
	v_lshlrev_b32_e32 v138, 16, v81
	v_and_b32_e32 v139, 0xffff0000, v81
	v_lshlrev_b32_e32 v140, 16, v82
	v_and_b32_e32 v141, 0xffff0000, v82
	v_lshlrev_b32_e32 v142, 16, v83
	v_and_b32_e32 v143, 0xffff0000, v83
	v_lshlrev_b32_e32 v144, 16, v84
	v_and_b32_e32 v145, 0xffff0000, v84
	v_lshlrev_b32_e32 v146, 16, v85
	v_and_b32_e32 v147, 0xffff0000, v85
	v_lshlrev_b32_e32 v148, 16, v86
	v_and_b32_e32 v149, 0xffff0000, v86
	v_lshlrev_b32_e32 v150, 16, v87
	v_and_b32_e32 v151, 0xffff0000, v87
	s_lshl_b32 s100, s10, 13
	s_mov_b32 s101, 0
	v_lshl_add_u64 v[164:165], v[4:5], 0, s[100:101]
	v_mul_f32_e32 v136, v136, v33
	v_mul_f32_e32 v137, v137, v33
	v_mul_f32_e32 v138, v138, v33
	v_mul_f32_e32 v139, v139, v33
	v_mul_f32_e32 v136, v64, v136
	v_mul_f32_e32 v137, v65, v137
	v_mul_f32_e32 v138, v66, v138
	v_mul_f32_e32 v139, v67, v139
	v_fma_f32 v136, v104, v136, v120
	v_fma_f32 v137, v105, v137, v121
	v_fma_f32 v138, v106, v138, v122
	v_fma_f32 v139, v107, v139, v123
	v_cvt_pk_bf16_f32 v166, v136, v137
	v_cvt_pk_bf16_f32 v167, v138, v139
	global_store_dwordx2 v[164:165], v[166:167], off offset:0
	v_mul_f32_e32 v140, v140, v33
	v_mul_f32_e32 v141, v141, v33
	v_mul_f32_e32 v142, v142, v33
	v_mul_f32_e32 v143, v143, v33
	v_mul_f32_e32 v140, v68, v140
	v_mul_f32_e32 v141, v69, v141
	v_mul_f32_e32 v142, v70, v142
	v_mul_f32_e32 v143, v71, v143
	v_fma_f32 v140, v108, v140, v124
	v_fma_f32 v141, v109, v141, v125
	v_fma_f32 v142, v110, v142, v126
	v_fma_f32 v143, v111, v143, v127
	v_cvt_pk_bf16_f32 v166, v140, v141
	v_cvt_pk_bf16_f32 v167, v142, v143
	global_store_dwordx2 v[164:165], v[166:167], off offset:512
	v_mul_f32_e32 v144, v144, v33
	v_mul_f32_e32 v145, v145, v33
	v_mul_f32_e32 v146, v146, v33
	v_mul_f32_e32 v147, v147, v33
	v_mul_f32_e32 v144, v72, v144
	v_mul_f32_e32 v145, v73, v145
	v_mul_f32_e32 v146, v74, v146
	v_mul_f32_e32 v147, v75, v147
	v_fma_f32 v144, v112, v144, v128
	v_fma_f32 v145, v113, v145, v129
	v_fma_f32 v146, v114, v146, v130
	v_fma_f32 v147, v115, v147, v131
	v_cvt_pk_bf16_f32 v166, v144, v145
	v_cvt_pk_bf16_f32 v167, v146, v147
	global_store_dwordx2 v[164:165], v[166:167], off offset:1024
	v_mul_f32_e32 v148, v148, v33
	v_mul_f32_e32 v149, v149, v33
	v_mul_f32_e32 v150, v150, v33
	v_mul_f32_e32 v151, v151, v33
	v_mul_f32_e32 v148, v76, v148
	v_mul_f32_e32 v149, v77, v149
	v_mul_f32_e32 v150, v78, v150
	v_mul_f32_e32 v151, v79, v151
	v_fma_f32 v148, v116, v148, v132
	v_fma_f32 v149, v117, v149, v133
	v_fma_f32 v150, v118, v150, v134
	v_fma_f32 v151, v119, v151, v135
	v_cvt_pk_bf16_f32 v166, v148, v149
	v_cvt_pk_bf16_f32 v167, v150, v151
	global_store_dwordx2 v[164:165], v[166:167], off offset:1536
	v_mov_b32_e32 v34, s17
	v_fmamk_f32 v34, v34, 0x3a800000, v14
	v_rsq_f32_e32 v33, v34
	v_lshlrev_b32_e32 v136, 16, v88
	v_and_b32_e32 v137, 0xffff0000, v88
	v_lshlrev_b32_e32 v138, 16, v89
	v_and_b32_e32 v139, 0xffff0000, v89
	v_lshlrev_b32_e32 v140, 16, v90
	v_and_b32_e32 v141, 0xffff0000, v90
	v_lshlrev_b32_e32 v142, 16, v91
	v_and_b32_e32 v143, 0xffff0000, v91
	v_lshlrev_b32_e32 v144, 16, v92
	v_and_b32_e32 v145, 0xffff0000, v92
	v_lshlrev_b32_e32 v146, 16, v93
	v_and_b32_e32 v147, 0xffff0000, v93
	v_lshlrev_b32_e32 v148, 16, v94
	v_and_b32_e32 v149, 0xffff0000, v94
	v_lshlrev_b32_e32 v150, 16, v95
	v_and_b32_e32 v151, 0xffff0000, v95
	s_lshl_b32 s100, s10, 13
	s_add_u32 s100, s100, 0x800
	s_mov_b32 s101, 0
	v_lshl_add_u64 v[164:165], v[4:5], 0, s[100:101]
	v_mul_f32_e32 v136, v136, v33
	v_mul_f32_e32 v137, v137, v33
	v_mul_f32_e32 v138, v138, v33
	v_mul_f32_e32 v139, v139, v33
	v_mul_f32_e32 v136, v64, v136
	v_mul_f32_e32 v137, v65, v137
	v_mul_f32_e32 v138, v66, v138
	v_mul_f32_e32 v139, v67, v139
	v_fma_f32 v136, v104, v136, v120
	v_fma_f32 v137, v105, v137, v121
	v_fma_f32 v138, v106, v138, v122
	v_fma_f32 v139, v107, v139, v123
	v_cvt_pk_bf16_f32 v166, v136, v137
	v_cvt_pk_bf16_f32 v167, v138, v139
	global_store_dwordx2 v[164:165], v[166:167], off offset:0
	v_mul_f32_e32 v140, v140, v33
	v_mul_f32_e32 v141, v141, v33
	v_mul_f32_e32 v142, v142, v33
	v_mul_f32_e32 v143, v143, v33
	v_mul_f32_e32 v140, v68, v140
	v_mul_f32_e32 v141, v69, v141
	v_mul_f32_e32 v142, v70, v142
	v_mul_f32_e32 v143, v71, v143
	v_fma_f32 v140, v108, v140, v124
	v_fma_f32 v141, v109, v141, v125
; __device__ __forceinline__ unsigned cvt_pk_bf16(float lo, float hi) { unsigned r; asm volatile("v_cvt_pk_bf16_f32 %0, %1, %2" : "=v"(r) : "v"(lo), "v"(hi)); return r; }
;     ...
;     if (F.gw >= wave0) for (int row = row_begin + (F.gw - wave0); row < nrows; row += F.NGW - wave0) {
;         const bool isctx = row >= NLAT; const int b = isctx ? 8 : (row >> 12);
;         const size_t roff = isctx ? (size_t)(row - NLAT) * DM : (size_t)row * DM; const void* sp = isctx ? src_ctx : src_lat;
;         f32x4 v[4]; float ss = 0.f;
;         if (SB) { const u32x2* xr = (const u32x2*)((const bf16*)sp + roff) + f_lane;
; #pragma unroll
;             for (int j = 0; j < 4; ++j) { const u32x2 r = xr[64 * j]; v[j] = (f32x4){__uint_as_float(r.x << 16), __uint_as_float(r.x & 0xffff0000u), __uint_as_float(r.y << 16), __uint_as_float(r.y & 0xffff0000u)}; } }
;         else { const f32x4* xr = (const f32x4*)((const float*)sp + roff) + f_lane;
; #pragma unroll
;             for (int j = 0; j < 4; ++j) v[j] = xr[64 * j]; }
;         if (part != nullptr && isctx) {
;             const f32x4* p0 = (const f32x4*)(part + (size_t)(row - NLAT) * DM) + f_lane; const f32x4* p1 = p0 + (size_t)NCTX * DM / 4; const f32x4* g4p = (const f32x4*)pgate + f_lane;
; #pragma unroll
;             for (int j = 0; j < 4; ++j) v[j] += g4p[64 * j] * (p0[64 * j] + p1[64 * j]); }
; #pragma unroll
;         for (int j = 0; j < 4; ++j) ss += (v[j].x * v[j].x + v[j].y * v[j].y) + (v[j].z * v[j].z + v[j].w * v[j].w);
;         const float rstd = rsqrtf(wave_sum(ss) * (1.0f / DM) + EPS);
;         const f32x4* g4 = (const f32x4*)gnorm + f_lane; const f32x4* sh4 = (const f32x4*)(modl + b * MODS + shc * DM) + f_lane; const f32x4* sc4 = (const f32x4*)(modl + b * MODS + scc * DM) + f_lane;
;         u32x2* o8 = (u32x2*)(H + (size_t)row * DM) + f_lane;
; #pragma unroll
;         for (int j = 0; j < 4; ++j) { const f32x4 y = v[j] * rstd * g4[64 * j] * (sc4[64 * j] + 1.0f) + sh4[64 * j];
;             u32x2 w; w.x = cvt_pk_bf16(y.x, y.y); w.y = cvt_pk_bf16(y.z, y.w); o8[64 * j] = w; }
	v_fma_f32 v142, v110, v142, v126
	v_fma_f32 v143, v111, v143, v127
	v_cvt_pk_bf16_f32 v166, v140, v141
	v_cvt_pk_bf16_f32 v167, v142, v143
	global_store_dwordx2 v[164:165], v[166:167], off offset:512
	v_mul_f32_e32 v144, v144, v33
	v_mul_f32_e32 v145, v145, v33
	v_mul_f32_e32 v146, v146, v33
	v_mul_f32_e32 v147, v147, v33
	v_mul_f32_e32 v144, v72, v144
	v_mul_f32_e32 v145, v73, v145
	v_mul_f32_e32 v146, v74, v146
	v_mul_f32_e32 v147, v75, v147
	v_fma_f32 v144, v112, v144, v128
	v_fma_f32 v145, v113, v145, v129
	v_fma_f32 v146, v114, v146, v130
	v_fma_f32 v147, v115, v147, v131
	v_cvt_pk_bf16_f32 v166, v144, v145
	v_cvt_pk_bf16_f32 v167, v146, v147
	global_store_dwordx2 v[164:165], v[166:167], off offset:1024
	v_mul_f32_e32 v148, v148, v33
	v_mul_f32_e32 v149, v149, v33
	v_mul_f32_e32 v150, v150, v33
	v_mul_f32_e32 v151, v151, v33
	v_mul_f32_e32 v148, v76, v148
	v_mul_f32_e32 v149, v77, v149
	v_mul_f32_e32 v150, v78, v150
	v_mul_f32_e32 v151, v79, v151
	v_fma_f32 v148, v116, v148, v132
	v_fma_f32 v149, v117, v149, v133
	v_fma_f32 v150, v118, v150, v134
	v_fma_f32 v151, v119, v151, v135
	v_cvt_pk_bf16_f32 v166, v148, v149
	v_cvt_pk_bf16_f32 v167, v150, v151
	global_store_dwordx2 v[164:165], v[166:167], off offset:1536
	v_mov_b32_e32 v34, vcc_lo
	v_fmamk_f32 v34, v34, 0x3a800000, v14
	v_rsq_f32_e32 v33, v34
	v_lshlrev_b32_e32 v136, 16, v96
	v_and_b32_e32 v137, 0xffff0000, v96
	v_lshlrev_b32_e32 v138, 16, v97
	v_and_b32_e32 v139, 0xffff0000, v97
	v_lshlrev_b32_e32 v140, 16, v98
	v_and_b32_e32 v141, 0xffff0000, v98
	v_lshlrev_b32_e32 v142, 16, v99
	v_and_b32_e32 v143, 0xffff0000, v99
	v_lshlrev_b32_e32 v144, 16, v100
	v_and_b32_e32 v145, 0xffff0000, v100
	v_lshlrev_b32_e32 v146, 16, v101
	v_and_b32_e32 v147, 0xffff0000, v101
	v_lshlrev_b32_e32 v148, 16, v102
	v_and_b32_e32 v149, 0xffff0000, v102
	v_lshlrev_b32_e32 v150, 16, v103
	v_and_b32_e32 v151, 0xffff0000, v103
	s_lshl_b32 s100, s10, 13
	s_add_u32 s100, s100, 0x1000
	s_mov_b32 s101, 0
	v_lshl_add_u64 v[164:165], v[4:5], 0, s[100:101]
	v_mul_f32_e32 v136, v136, v33
	v_mul_f32_e32 v137, v137, v33
	v_mul_f32_e32 v138, v138, v33
	v_mul_f32_e32 v139, v139, v33
	v_mul_f32_e32 v136, v64, v136
	v_mul_f32_e32 v137, v65, v137
	v_mul_f32_e32 v138, v66, v138
	v_mul_f32_e32 v139, v67, v139
	v_fma_f32 v136, v104, v136, v120
	v_fma_f32 v137, v105, v137, v121
	v_fma_f32 v138, v106, v138, v122
	v_fma_f32 v139, v107, v139, v123
	v_cvt_pk_bf16_f32 v166, v136, v137
	v_cvt_pk_bf16_f32 v167, v138, v139
	global_store_dwordx2 v[164:165], v[166:167], off offset:0
	v_mul_f32_e32 v140, v140, v33
	v_mul_f32_e32 v141, v141, v33
	v_mul_f32_e32 v142, v142, v33
	v_mul_f32_e32 v143, v143, v33
	v_mul_f32_e32 v140, v68, v140
	v_mul_f32_e32 v141, v69, v141
	v_mul_f32_e32 v142, v70, v142
	v_mul_f32_e32 v143, v71, v143
	v_fma_f32 v140, v108, v140, v124
	v_fma_f32 v141, v109, v141, v125
	v_fma_f32 v142, v110, v142, v126
	v_fma_f32 v143, v111, v143, v127
	v_cvt_pk_bf16_f32 v166, v140, v141
	v_cvt_pk_bf16_f32 v167, v142, v143
	global_store_dwordx2 v[164:165], v[166:167], off offset:512
	v_mul_f32_e32 v144, v144, v33
	v_mul_f32_e32 v145, v145, v33
	v_mul_f32_e32 v146, v146, v33
	v_mul_f32_e32 v147, v147, v33
	v_mul_f32_e32 v144, v72, v144
	v_mul_f32_e32 v145, v73, v145
	v_mul_f32_e32 v146, v74, v146
	v_mul_f32_e32 v147, v75, v147
	v_fma_f32 v144, v112, v144, v128
	v_fma_f32 v145, v113, v145, v129
	v_fma_f32 v146, v114, v146, v130
	v_fma_f32 v147, v115, v147, v131
	v_cvt_pk_bf16_f32 v166, v144, v145
	v_cvt_pk_bf16_f32 v167, v146, v147
	global_store_dwordx2 v[164:165], v[166:167], off offset:1024
	v_mul_f32_e32 v148, v148, v33
	v_mul_f32_e32 v149, v149, v33
	v_mul_f32_e32 v150, v150, v33
	v_mul_f32_e32 v151, v151, v33
	v_mul_f32_e32 v148, v76, v148
	v_mul_f32_e32 v149, v77, v149
	v_mul_f32_e32 v150, v78, v150
	v_mul_f32_e32 v151, v79, v151
	v_fma_f32 v148, v116, v148, v132
	v_fma_f32 v149, v117, v149, v133
	v_fma_f32 v150, v118, v150, v134
	v_fma_f32 v151, v119, v151, v135
	v_cvt_pk_bf16_f32 v166, v148, v149
	v_cvt_pk_bf16_f32 v167, v150, v151
	global_store_dwordx2 v[164:165], v[166:167], off offset:1536
	v_mov_b32_e32 v34, vcc_hi
	v_fmamk_f32 v34, v34, 0x3a800000, v14
	v_rsq_f32_e32 v33, v34
	v_lshlrev_b32_e32 v136, 16, v156
	v_and_b32_e32 v137, 0xffff0000, v156
	v_lshlrev_b32_e32 v138, 16, v157
	v_and_b32_e32 v139, 0xffff0000, v157
	v_lshlrev_b32_e32 v140, 16, v158
	v_and_b32_e32 v141, 0xffff0000, v158
	v_lshlrev_b32_e32 v142, 16, v159
	v_and_b32_e32 v143, 0xffff0000, v159
	v_lshlrev_b32_e32 v144, 16, v160
	v_and_b32_e32 v145, 0xffff0000, v160
	v_lshlrev_b32_e32 v146, 16, v161
	v_and_b32_e32 v147, 0xffff0000, v161
	v_lshlrev_b32_e32 v148, 16, v162
	v_and_b32_e32 v149, 0xffff0000, v162
	v_lshlrev_b32_e32 v150, 16, v163
	v_and_b32_e32 v151, 0xffff0000, v163
	s_lshl_b32 s100, s10, 13
	s_add_u32 s100, s100, 0x1800
	s_mov_b32 s101, 0
	v_lshl_add_u64 v[164:165], v[4:5], 0, s[100:101]
	v_mul_f32_e32 v136, v136, v33
	v_mul_f32_e32 v137, v137, v33
	v_mul_f32_e32 v138, v138, v33
	v_mul_f32_e32 v139, v139, v33
	v_mul_f32_e32 v136, v64, v136
	v_mul_f32_e32 v137, v65, v137
	v_mul_f32_e32 v138, v66, v138
	v_mul_f32_e32 v139, v67, v139
	v_fma_f32 v136, v104, v136, v120
	v_fma_f32 v137, v105, v137, v121
	v_fma_f32 v138, v106, v138, v122
	v_fma_f32 v139, v107, v139, v123
	v_cvt_pk_bf16_f32 v166, v136, v137
	v_cvt_pk_bf16_f32 v167, v138, v139
	global_store_dwordx2 v[164:165], v[166:167], off offset:0
	v_mul_f32_e32 v140, v140, v33
	v_mul_f32_e32 v141, v141, v33
	v_mul_f32_e32 v142, v142, v33
	v_mul_f32_e32 v143, v143, v33
	v_mul_f32_e32 v140, v68, v140
	v_mul_f32_e32 v141, v69, v141
	v_mul_f32_e32 v142, v70, v142
	v_mul_f32_e32 v143, v71, v143
	v_fma_f32 v140, v108, v140, v124
	v_fma_f32 v141, v109, v141, v125
	v_fma_f32 v142, v110, v142, v126
	v_fma_f32 v143, v111, v143, v127
	v_cvt_pk_bf16_f32 v166, v140, v141
	v_cvt_pk_bf16_f32 v167, v142, v143
	global_store_dwordx2 v[164:165], v[166:167], off offset:512
	v_mul_f32_e32 v144, v144, v33
	v_mul_f32_e32 v145, v145, v33
	v_mul_f32_e32 v146, v146, v33
	v_mul_f32_e32 v147, v147, v33
	v_mul_f32_e32 v144, v72, v144
	v_mul_f32_e32 v145, v73, v145
	v_mul_f32_e32 v146, v74, v146
	v_mul_f32_e32 v147, v75, v147
	v_fma_f32 v144, v112, v144, v128
	v_fma_f32 v145, v113, v145, v129
	v_fma_f32 v146, v114, v146, v130
	v_fma_f32 v147, v115, v147, v131
	v_cvt_pk_bf16_f32 v166, v144, v145
	v_cvt_pk_bf16_f32 v167, v146, v147
	global_store_dwordx2 v[164:165], v[166:167], off offset:1024
	v_mul_f32_e32 v148, v148, v33
	v_mul_f32_e32 v149, v149, v33
	v_mul_f32_e32 v150, v150, v33
	v_mul_f32_e32 v151, v151, v33
	v_mul_f32_e32 v148, v76, v148
	v_mul_f32_e32 v149, v77, v149
	v_mul_f32_e32 v150, v78, v150
	v_mul_f32_e32 v151, v79, v151
	v_fma_f32 v148, v116, v148, v132
	v_fma_f32 v149, v117, v149, v133
	v_fma_f32 v150, v118, v150, v134
	v_fma_f32 v151, v119, v151, v135
	v_cvt_pk_bf16_f32 v166, v148, v149
	v_cvt_pk_bf16_f32 v167, v150, v151
	global_store_dwordx2 v[164:165], v[166:167], off offset:1536
	s_add_i32 s10, s10, s5
	s_lshl_b32 s11, s10, 2
	s_cmp_lt_i32 s11, 0x8000
	s_cbranch_scc1 .Lmn4_p8_blk
;     ...
;     if (F.gw >= wave0) for (int row = row_begin + (F.gw - wave0); row < nrows; row += F.NGW - wave0) {
.Lmn4_p8_done:
.Lmn4_p8_fin:
	s_add_i32 s4, s4, s5
	s_cmp_lt_i32 s4, 0x8000
	s_cbranch_scc1 .Lmn4_p8_fin

; __device__ __forceinline__ const float* inp(int k) { const CAS cfptr* p = (const CAS cfptr*)__builtin_amdgcn_kernarg_segment_ptr(); asm volatile("" : "+s"(p)); return p[k]; }
; #define LANE_IDS() const int f_tid = tid_(); const int f_lane = f_tid & 63; const int f_gtid = blockIdx.x * (NWAVES * 64) + f_tid; (void)f_lane; (void)f_gtid
;     LANE_IDS();
;     if (F.gw >= wave0) for (int row = row_begin + (F.gw - wave0); row < nrows; row += F.NGW - wave0) {
;         const bool isctx = row >= NLAT; const int b = isctx ? 8 : (row >> 12);
;         const size_t roff = isctx ? (size_t)(row - NLAT) * DM : (size_t)row * DM; const void* sp = isctx ? src_ctx : src_lat;
;         f32x4 v[4]; float ss = 0.f;
;         if (SB) { const u32x2* xr = (const u32x2*)((const bf16*)sp + roff) + f_lane;
; #pragma unroll
;             for (int j = 0; j < 4; ++j) { const u32x2 r = xr[64 * j]; v[j] = (f32x4){__uint_as_float(r.x << 16), __uint_as_float(r.x & 0xffff0000u), __uint_as_float(r.y << 16), __uint_as_float(r.y & 0xffff0000u)}; } }
;         else { const f32x4* xr = (const f32x4*)((const float*)sp + roff) + f_lane;
; #pragma unroll
;             for (int j = 0; j < 4; ++j) v[j] = xr[64 * j]; }
; __global__ void __launch_bounds__(NWAVES * 64, 2) mk_fwd(Args args) {
;     ...
;         if (bx >= 2 * NCB) modnorm_rows<true>(F, X, X + (size_t)NLAT * DM, NLAT, H, inp(6) + DM, mod1, 0, 1, nullptr, nullptr, 0, 2 * NCB * NWAVES);
.LBB0_1105:
	s_waitcnt lgkmcnt(0)
	s_add_u32 s3, s52, 0x37000
	s_addc_u32 s33, s53, 0
	s_add_u32 s44, s52, 0x6000000
	s_addc_u32 s45, s53, 0
	s_add_u32 s86, s52, 0xe800000
	s_mov_b64 s[22:23], s[80:81]
	s_addc_u32 s87, s53, 0
	s_andn2_b64 vcc, exec, s[8:9]
	s_cbranch_vccnz .LBB0_1109
	s_lshl_b32 s12, s84, 4
	s_cmp_lt_i32 s46, s12
	s_cselect_b64 s[8:9], -1, 0
	s_sub_i32 s4, s46, s12
	s_cmpk_gt_i32 s4, 0x7fff
	s_cselect_b64 s[10:11], -1, 0
	s_or_b64 s[8:9], s[8:9], s[10:11]
	s_mov_b64 s[6:7], s[0:1]
	v_mov_b32_e32 v0, v188
	s_and_b64 vcc, exec, s[8:9]
	s_cbranch_vccnz .LBB0_1109
	v_and_b32_e32 v16, 63, v0
	v_mbcnt_lo_u32_b32 v0, -1, 0
	v_mbcnt_hi_u32_b32 v0, -1, v0
	v_and_b32_e32 v2, 64, v0
	v_add_u32_e32 v2, 64, v2
	v_xor_b32_e32 v3, 1, v0
	v_cmp_lt_i32_e32 vcc, v3, v2
	s_load_dwordx2 s[6:7], s[6:7], 0x30
	v_mov_b32_e32 v1, 0
	v_cndmask_b32_e32 v3, v0, v3, vcc
	v_lshlrev_b32_e32 v8, 2, v3
	v_xor_b32_e32 v3, 2, v0
	v_cmp_lt_i32_e32 vcc, v3, v2
	v_mov_b32_e32 v14, 0x358637bd
	s_mov_b32 s13, 0x800000
	v_cndmask_b32_e32 v3, v0, v3, vcc
	v_lshlrev_b32_e32 v9, 2, v3
	v_xor_b32_e32 v3, 4, v0
	v_cmp_lt_i32_e32 vcc, v3, v2
	s_movk_i32 s14, 0x1000
	v_readlane_b32 s16, v251, 5
	v_cndmask_b32_e32 v3, v0, v3, vcc
	v_lshlrev_b32_e32 v10, 2, v3
	v_xor_b32_e32 v3, 8, v0
	v_cmp_lt_i32_e32 vcc, v3, v2
	v_readlane_b32 s17, v251, 6
	s_nop 0
	v_cndmask_b32_e32 v3, v0, v3, vcc
	v_lshlrev_b32_e32 v11, 2, v3
	v_xor_b32_e32 v3, 16, v0
	v_cmp_lt_i32_e32 vcc, v3, v2
	s_nop 1
	v_cndmask_b32_e32 v3, v0, v3, vcc
	v_lshlrev_b32_e32 v12, 2, v3
	v_xor_b32_e32 v3, 32, v0
	v_cmp_lt_i32_e32 vcc, v3, v2
	s_nop 1
	v_cndmask_b32_e32 v0, v0, v3, vcc
	v_lshlrev_b32_e32 v13, 2, v0
	v_lshlrev_b32_e32 v0, 4, v16
	s_waitcnt lgkmcnt(0)
	v_lshl_add_u64 v[2:3], s[6:7], 0, v[0:1]
	s_mov_b64 s[6:7], 0x1000
	v_lshlrev_b32_e32 v0, 3, v16
	v_lshl_add_u64 v[2:3], v[2:3], 0, s[6:7]
	v_lshl_add_u64 v[4:5], s[86:87], 0, v[0:1]
	v_lshl_add_u64 v[6:7], s[44:45], 0, v[0:1]
	v_lshlrev_b32_e32 v0, 4, v16
	s_sub_i32 s5, s16, s12
	global_load_dwordx4 v[64:67], v[2:3], off offset:0
	global_load_dwordx4 v[68:71], v[2:3], off offset:1024
	global_load_dwordx4 v[72:75], v[2:3], off offset:2048
	global_load_dwordx4 v[76:79], v[2:3], off offset:3072
	s_mov_b32 s8, s4
	s_lshl_b32 s9, s8, 2
	s_cmp_lt_i32 s9, 0x8000
	s_cbranch_scc0 .Lmn4_p11_done
.Lmn4_p11_blk:
	s_ashr_i32 s100, s8, 10
	s_mul_i32 s100, s100, 0x6000
	s_add_u32 s100, s3, s100
	s_addc_u32 s101, s33, 0
	s_add_u32 s10, s100, 0x1000
	s_addc_u32 s11, s101, 0
	v_lshl_add_u64 v[136:137], s[10:11], 0, v[0:1]
	global_load_dwordx4 v[104:107], v[136:137], off offset:0
	global_load_dwordx4 v[108:111], v[136:137], off offset:1024
	global_load_dwordx4 v[112:115], v[136:137], off offset:2048
	global_load_dwordx4 v[116:119], v[136:137], off offset:3072
	v_lshl_add_u64 v[138:139], s[100:101], 0, v[0:1]
	global_load_dwordx4 v[120:123], v[138:139], off offset:0
	global_load_dwordx4 v[124:127], v[138:139], off offset:1024
	global_load_dwordx4 v[128:131], v[138:139], off offset:2048
	global_load_dwordx4 v[132:135], v[138:139], off offset:3072
	s_lshl_b32 s100, s8, 13
	s_mov_b32 s101, 0
	v_lshl_add_u64 v[164:165], v[6:7], 0, s[100:101]
	global_load_dwordx2 v[80:81], v[164:165], off offset:0
	global_load_dwordx2 v[82:83], v[164:165], off offset:512
	global_load_dwordx2 v[84:85], v[164:165], off offset:1024
	global_load_dwordx2 v[86:87], v[164:165], off offset:1536
	s_lshl_b32 s100, s8, 13
	s_add_u32 s100, s100, 0x800
	s_mov_b32 s101, 0
	v_lshl_add_u64 v[164:165], v[6:7], 0, s[100:101]
	global_load_dwordx2 v[88:89], v[164:165], off offset:0
	global_load_dwordx2 v[90:91], v[164:165], off offset:512
	global_load_dwordx2 v[92:93], v[164:165], off offset:1024
	global_load_dwordx2 v[94:95], v[164:165], off offset:1536
	s_lshl_b32 s100, s8, 13
	s_add_u32 s100, s100, 0x1000
	s_mov_b32 s101, 0
	v_lshl_add_u64 v[164:165], v[6:7], 0, s[100:101]
	global_load_dwordx2 v[96:97], v[164:165], off offset:0
	global_load_dwordx2 v[98:99], v[164:165], off offset:512
	global_load_dwordx2 v[100:101], v[164:165], off offset:1024
	global_load_dwordx2 v[102:103], v[164:165], off offset:1536
	s_lshl_b32 s100, s8, 13
	s_add_u32 s100, s100, 0x1800
	s_mov_b32 s101, 0
	v_lshl_add_u64 v[164:165], v[6:7], 0, s[100:101]
	global_load_dwordx2 v[156:157], v[164:165], off offset:0
	global_load_dwordx2 v[158:159], v[164:165], off offset:512
	global_load_dwordx2 v[160:161], v[164:165], off offset:1024
	global_load_dwordx2 v[162:163], v[164:165], off offset:1536
	s_waitcnt vmcnt(0)
;     ...
;         if (SB) { const u32x2* xr = (const u32x2*)((const bf16*)sp + roff) + f_lane;
; #pragma unroll
;             for (int j = 0; j < 4; ++j) { const u32x2 r = xr[64 * j]; v[j] = (f32x4){__uint_as_float(r.x << 16), __uint_as_float(r.x & 0xffff0000u), __uint_as_float(r.y << 16), __uint_as_float(r.y & 0xffff0000u)}; } }
;         else { const f32x4* xr = (const f32x4*)((const float*)sp + roff) + f_lane;
; #pragma unroll
;             for (int j = 0; j < 4; ++j) v[j] = xr[64 * j]; }
;         if (part != nullptr && isctx) {
;             const f32x4* p0 = (const f32x4*)(part + (size_t)(row - NLAT) * DM) + f_lane; const f32x4* p1 = p0 + (size_t)NCTX * DM / 4; const f32x4* g4p = (const f32x4*)pgate + f_lane;
; #pragma unroll
;             for (int j = 0; j < 4; ++j) v[j] += g4p[64 * j] * (p0[64 * j] + p1[64 * j]); }
; #pragma unroll
;         for (int j = 0; j < 4; ++j) ss += (v[j].x * v[j].x + v[j].y * v[j].y) + (v[j].z * v[j].z + v[j].w * v[j].w);
;         const float rstd = rsqrtf(wave_sum(ss) * (1.0f / DM) + EPS);
	v_add_f32_e32 v104, 1.0, v104
	v_add_f32_e32 v105, 1.0, v105
	v_add_f32_e32 v106, 1.0, v106
	v_add_f32_e32 v107, 1.0, v107
	v_add_f32_e32 v108, 1.0, v108
	v_add_f32_e32 v109, 1.0, v109
	v_add_f32_e32 v110, 1.0, v110
	v_add_f32_e32 v111, 1.0, v111
	v_add_f32_e32 v112, 1.0, v112
	v_add_f32_e32 v113, 1.0, v113
	v_add_f32_e32 v114, 1.0, v114
	v_add_f32_e32 v115, 1.0, v115
	v_add_f32_e32 v116, 1.0, v116
	v_add_f32_e32 v117, 1.0, v117
	v_add_f32_e32 v118, 1.0, v118
	v_add_f32_e32 v119, 1.0, v119
	v_lshlrev_b32_e32 v136, 16, v80
	v_and_b32_e32 v137, 0xffff0000, v80
	v_lshlrev_b32_e32 v138, 16, v81
	v_and_b32_e32 v139, 0xffff0000, v81
	v_lshlrev_b32_e32 v140, 16, v82
	v_and_b32_e32 v141, 0xffff0000, v82
	v_lshlrev_b32_e32 v142, 16, v83
	v_and_b32_e32 v143, 0xffff0000, v83
	v_lshlrev_b32_e32 v144, 16, v84
	v_and_b32_e32 v145, 0xffff0000, v84
	v_lshlrev_b32_e32 v146, 16, v85
	v_and_b32_e32 v147, 0xffff0000, v85
	v_lshlrev_b32_e32 v148, 16, v86
	v_and_b32_e32 v149, 0xffff0000, v86
	v_lshlrev_b32_e32 v150, 16, v87
	v_and_b32_e32 v151, 0xffff0000, v87
	v_mul_f32_e32 v28, v136, v136
	v_mul_f32_e32 v32, v137, v137
	v_fmac_f32_e32 v28, v138, v138
	v_fmac_f32_e32 v32, v139, v139
	v_fmac_f32_e32 v28, v140, v140
	v_fmac_f32_e32 v32, v141, v141
	v_fmac_f32_e32 v28, v142, v142
	v_fmac_f32_e32 v32, v143, v143
	v_fmac_f32_e32 v28, v144, v144
	v_fmac_f32_e32 v32, v145, v145
	v_fmac_f32_e32 v28, v146, v146
	v_fmac_f32_e32 v32, v147, v147
	v_fmac_f32_e32 v28, v148, v148
	v_fmac_f32_e32 v32, v149, v149
	v_fmac_f32_e32 v28, v150, v150
	v_fmac_f32_e32 v32, v151, v151
	v_add_f32_e32 v28, v28, v32
	v_lshlrev_b32_e32 v136, 16, v88
	v_and_b32_e32 v137, 0xffff0000, v88
	v_lshlrev_b32_e32 v138, 16, v89
	v_and_b32_e32 v139, 0xffff0000, v89
	v_lshlrev_b32_e32 v140, 16, v90
	v_and_b32_e32 v141, 0xffff0000, v90
	v_lshlrev_b32_e32 v142, 16, v91
	v_and_b32_e32 v143, 0xffff0000, v91
	v_lshlrev_b32_e32 v144, 16, v92
	v_and_b32_e32 v145, 0xffff0000, v92
	v_lshlrev_b32_e32 v146, 16, v93
	v_and_b32_e32 v147, 0xffff0000, v93
	v_lshlrev_b32_e32 v148, 16, v94
	v_and_b32_e32 v149, 0xffff0000, v94
	v_lshlrev_b32_e32 v150, 16, v95
	v_and_b32_e32 v151, 0xffff0000, v95
	v_mul_f32_e32 v29, v136, v136
	v_mul_f32_e32 v32, v137, v137
	v_fmac_f32_e32 v29, v138, v138
	v_fmac_f32_e32 v32, v139, v139
	v_fmac_f32_e32 v29, v140, v140
	v_fmac_f32_e32 v32, v141, v141
	v_fmac_f32_e32 v29, v142, v142
	v_fmac_f32_e32 v32, v143, v143
	v_fmac_f32_e32 v29, v144, v144
	v_fmac_f32_e32 v32, v145, v145
	v_fmac_f32_e32 v29, v146, v146
	v_fmac_f32_e32 v32, v147, v147
	v_fmac_f32_e32 v29, v148, v148
	v_fmac_f32_e32 v32, v149, v149
	v_fmac_f32_e32 v29, v150, v150
	v_fmac_f32_e32 v32, v151, v151
	v_add_f32_e32 v29, v29, v32
	v_lshlrev_b32_e32 v136, 16, v96
	v_and_b32_e32 v137, 0xffff0000, v96
	v_lshlrev_b32_e32 v138, 16, v97
	v_and_b32_e32 v139, 0xffff0000, v97
	v_lshlrev_b32_e32 v140, 16, v98
	v_and_b32_e32 v141, 0xffff0000, v98
	v_lshlrev_b32_e32 v142, 16, v99
	v_and_b32_e32 v143, 0xffff0000, v99
	v_lshlrev_b32_e32 v144, 16, v100
	v_and_b32_e32 v145, 0xffff0000, v100
	v_lshlrev_b32_e32 v146, 16, v101
	v_and_b32_e32 v147, 0xffff0000, v101
	v_lshlrev_b32_e32 v148, 16, v102
	v_and_b32_e32 v149, 0xffff0000, v102
	v_lshlrev_b32_e32 v150, 16, v103
	v_and_b32_e32 v151, 0xffff0000, v103
	v_mul_f32_e32 v30, v136, v136
	v_mul_f32_e32 v32, v137, v137
	v_fmac_f32_e32 v30, v138, v138
	v_fmac_f32_e32 v32, v139, v139
	v_fmac_f32_e32 v30, v140, v140
	v_fmac_f32_e32 v32, v141, v141
	v_fmac_f32_e32 v30, v142, v142
	v_fmac_f32_e32 v32, v143, v143
	v_fmac_f32_e32 v30, v144, v144
	v_fmac_f32_e32 v32, v145, v145
	v_fmac_f32_e32 v30, v146, v146
	v_fmac_f32_e32 v32, v147, v147
	v_fmac_f32_e32 v30, v148, v148
	v_fmac_f32_e32 v32, v149, v149
	v_fmac_f32_e32 v30, v150, v150
	v_fmac_f32_e32 v32, v151, v151
	v_add_f32_e32 v30, v30, v32
	v_lshlrev_b32_e32 v136, 16, v156
	v_and_b32_e32 v137, 0xffff0000, v156
	v_lshlrev_b32_e32 v138, 16, v157
	v_and_b32_e32 v139, 0xffff0000, v157
	v_lshlrev_b32_e32 v140, 16, v158
	v_and_b32_e32 v141, 0xffff0000, v158
	v_lshlrev_b32_e32 v142, 16, v159
	v_and_b32_e32 v143, 0xffff0000, v159
	v_lshlrev_b32_e32 v144, 16, v160
	v_and_b32_e32 v145, 0xffff0000, v160
	v_lshlrev_b32_e32 v146, 16, v161
	v_and_b32_e32 v147, 0xffff0000, v161
	v_lshlrev_b32_e32 v148, 16, v162
	v_and_b32_e32 v149, 0xffff0000, v162
	v_lshlrev_b32_e32 v150, 16, v163
	v_and_b32_e32 v151, 0xffff0000, v163
	v_mul_f32_e32 v31, v136, v136
	v_mul_f32_e32 v32, v137, v137
	v_fmac_f32_e32 v31, v138, v138
	v_fmac_f32_e32 v32, v139, v139
	v_fmac_f32_e32 v31, v140, v140
	v_fmac_f32_e32 v32, v141, v141
	v_fmac_f32_e32 v31, v142, v142
	v_fmac_f32_e32 v32, v143, v143
	v_fmac_f32_e32 v31, v144, v144
	v_fmac_f32_e32 v32, v145, v145
	v_fmac_f32_e32 v31, v146, v146
	v_fmac_f32_e32 v32, v147, v147
	v_fmac_f32_e32 v31, v148, v148
	v_fmac_f32_e32 v32, v149, v149
	v_fmac_f32_e32 v31, v150, v150
	v_fmac_f32_e32 v32, v151, v151
	v_add_f32_e32 v31, v31, v32
	v_add_f32_dpp v28, v28, v28 row_shr:1 row_mask:0xf bank_mask:0xf bound_ctrl:0
	v_add_f32_dpp v29, v29, v29 row_shr:1 row_mask:0xf bank_mask:0xf bound_ctrl:0
	v_add_f32_dpp v30, v30, v30 row_shr:1 row_mask:0xf bank_mask:0xf bound_ctrl:0
	v_add_f32_dpp v31, v31, v31 row_shr:1 row_mask:0xf bank_mask:0xf bound_ctrl:0
	v_add_f32_dpp v28, v28, v28 row_shr:2 row_mask:0xf bank_mask:0xf bound_ctrl:0
	v_add_f32_dpp v29, v29, v29 row_shr:2 row_mask:0xf bank_mask:0xf bound_ctrl:0
	v_add_f32_dpp v30, v30, v30 row_shr:2 row_mask:0xf bank_mask:0xf bound_ctrl:0
	v_add_f32_dpp v31, v31, v31 row_shr:2 row_mask:0xf bank_mask:0xf bound_ctrl:0
	v_add_f32_dpp v28, v28, v28 row_shr:4 row_mask:0xf bank_mask:0xf bound_ctrl:0
; __device__ __forceinline__ unsigned cvt_pk_bf16(float lo, float hi) { unsigned r; asm volatile("v_cvt_pk_bf16_f32 %0, %1, %2" : "=v"(r) : "v"(lo), "v"(hi)); return r; }
;     ...
;         const float rstd = rsqrtf(wave_sum(ss) * (1.0f / DM) + EPS);
;         const f32x4* g4 = (const f32x4*)gnorm + f_lane; const f32x4* sh4 = (const f32x4*)(modl + b * MODS + shc * DM) + f_lane; const f32x4* sc4 = (const f32x4*)(modl + b * MODS + scc * DM) + f_lane;
;         u32x2* o8 = (u32x2*)(H + (size_t)row * DM) + f_lane;
; #pragma unroll
;         for (int j = 0; j < 4; ++j) { const f32x4 y = v[j] * rstd * g4[64 * j] * (sc4[64 * j] + 1.0f) + sh4[64 * j];
;             u32x2 w; w.x = cvt_pk_bf16(y.x, y.y); w.y = cvt_pk_bf16(y.z, y.w); o8[64 * j] = w; }
	v_add_f32_dpp v29, v29, v29 row_shr:4 row_mask:0xf bank_mask:0xf bound_ctrl:0
	v_add_f32_dpp v30, v30, v30 row_shr:4 row_mask:0xf bank_mask:0xf bound_ctrl:0
	v_add_f32_dpp v31, v31, v31 row_shr:4 row_mask:0xf bank_mask:0xf bound_ctrl:0
	v_add_f32_dpp v28, v28, v28 row_shr:8 row_mask:0xf bank_mask:0xf bound_ctrl:0
	v_add_f32_dpp v29, v29, v29 row_shr:8 row_mask:0xf bank_mask:0xf bound_ctrl:0
	v_add_f32_dpp v30, v30, v30 row_shr:8 row_mask:0xf bank_mask:0xf bound_ctrl:0
	v_add_f32_dpp v31, v31, v31 row_shr:8 row_mask:0xf bank_mask:0xf bound_ctrl:0
	v_add_f32_dpp v28, v28, v28 row_bcast:15 row_mask:0xa bank_mask:0xf
	v_add_f32_dpp v29, v29, v29 row_bcast:15 row_mask:0xa bank_mask:0xf
	v_add_f32_dpp v30, v30, v30 row_bcast:15 row_mask:0xa bank_mask:0xf
	v_add_f32_dpp v31, v31, v31 row_bcast:15 row_mask:0xa bank_mask:0xf
	v_add_f32_dpp v28, v28, v28 row_bcast:31 row_mask:0xc bank_mask:0xf
	v_add_f32_dpp v29, v29, v29 row_bcast:31 row_mask:0xc bank_mask:0xf
	v_add_f32_dpp v30, v30, v30 row_bcast:31 row_mask:0xc bank_mask:0xf
	v_add_f32_dpp v31, v31, v31 row_bcast:31 row_mask:0xc bank_mask:0xf
	s_nop 0
	v_readlane_b32 s10, v28, 63
	v_readlane_b32 s11, v29, 63
	v_readlane_b32 vcc_lo, v30, 63
	v_readlane_b32 vcc_hi, v31, 63
	v_mov_b32_e32 v34, s10
	v_fmamk_f32 v34, v34, 0x3a800000, v14
	v_rsq_f32_e32 v33, v34
	v_lshlrev_b32_e32 v136, 16, v80
	v_and_b32_e32 v137, 0xffff0000, v80
	v_lshlrev_b32_e32 v138, 16, v81
	v_and_b32_e32 v139, 0xffff0000, v81
	v_lshlrev_b32_e32 v140, 16, v82
	v_and_b32_e32 v141, 0xffff0000, v82
	v_lshlrev_b32_e32 v142, 16, v83
	v_and_b32_e32 v143, 0xffff0000, v83
	v_lshlrev_b32_e32 v144, 16, v84
	v_and_b32_e32 v145, 0xffff0000, v84
	v_lshlrev_b32_e32 v146, 16, v85
	v_and_b32_e32 v147, 0xffff0000, v85
	v_lshlrev_b32_e32 v148, 16, v86
	v_and_b32_e32 v149, 0xffff0000, v86
	v_lshlrev_b32_e32 v150, 16, v87
	v_and_b32_e32 v151, 0xffff0000, v87
	s_lshl_b32 s100, s8, 13
	s_mov_b32 s101, 0
	v_lshl_add_u64 v[164:165], v[4:5], 0, s[100:101]
	v_mul_f32_e32 v136, v136, v33
	v_mul_f32_e32 v137, v137, v33
	v_mul_f32_e32 v138, v138, v33
	v_mul_f32_e32 v139, v139, v33
	v_mul_f32_e32 v136, v64, v136
	v_mul_f32_e32 v137, v65, v137
	v_mul_f32_e32 v138, v66, v138
	v_mul_f32_e32 v139, v67, v139
	v_fma_f32 v136, v104, v136, v120
	v_fma_f32 v137, v105, v137, v121
	v_fma_f32 v138, v106, v138, v122
	v_fma_f32 v139, v107, v139, v123
	v_cvt_pk_bf16_f32 v166, v136, v137
	v_cvt_pk_bf16_f32 v167, v138, v139
	global_store_dwordx2 v[164:165], v[166:167], off offset:0
	v_mul_f32_e32 v140, v140, v33
	v_mul_f32_e32 v141, v141, v33
	v_mul_f32_e32 v142, v142, v33
	v_mul_f32_e32 v143, v143, v33
	v_mul_f32_e32 v140, v68, v140
	v_mul_f32_e32 v141, v69, v141
	v_mul_f32_e32 v142, v70, v142
	v_mul_f32_e32 v143, v71, v143
	v_fma_f32 v140, v108, v140, v124
	v_fma_f32 v141, v109, v141, v125
	v_fma_f32 v142, v110, v142, v126
	v_fma_f32 v143, v111, v143, v127
	v_cvt_pk_bf16_f32 v166, v140, v141
	v_cvt_pk_bf16_f32 v167, v142, v143
	global_store_dwordx2 v[164:165], v[166:167], off offset:512
	v_mul_f32_e32 v144, v144, v33
	v_mul_f32_e32 v145, v145, v33
	v_mul_f32_e32 v146, v146, v33
	v_mul_f32_e32 v147, v147, v33
	v_mul_f32_e32 v144, v72, v144
	v_mul_f32_e32 v145, v73, v145
	v_mul_f32_e32 v146, v74, v146
	v_mul_f32_e32 v147, v75, v147
	v_fma_f32 v144, v112, v144, v128
	v_fma_f32 v145, v113, v145, v129
	v_fma_f32 v146, v114, v146, v130
	v_fma_f32 v147, v115, v147, v131
	v_cvt_pk_bf16_f32 v166, v144, v145
	v_cvt_pk_bf16_f32 v167, v146, v147
	global_store_dwordx2 v[164:165], v[166:167], off offset:1024
	v_mul_f32_e32 v148, v148, v33
	v_mul_f32_e32 v149, v149, v33
	v_mul_f32_e32 v150, v150, v33
	v_mul_f32_e32 v151, v151, v33
	v_mul_f32_e32 v148, v76, v148
	v_mul_f32_e32 v149, v77, v149
	v_mul_f32_e32 v150, v78, v150
	v_mul_f32_e32 v151, v79, v151
	v_fma_f32 v148, v116, v148, v132
	v_fma_f32 v149, v117, v149, v133
	v_fma_f32 v150, v118, v150, v134
	v_fma_f32 v151, v119, v151, v135
	v_cvt_pk_bf16_f32 v166, v148, v149
	v_cvt_pk_bf16_f32 v167, v150, v151
	global_store_dwordx2 v[164:165], v[166:167], off offset:1536
	v_mov_b32_e32 v34, s11
	v_fmamk_f32 v34, v34, 0x3a800000, v14
	v_rsq_f32_e32 v33, v34
	v_lshlrev_b32_e32 v136, 16, v88
	v_and_b32_e32 v137, 0xffff0000, v88
	v_lshlrev_b32_e32 v138, 16, v89
	v_and_b32_e32 v139, 0xffff0000, v89
	v_lshlrev_b32_e32 v140, 16, v90
	v_and_b32_e32 v141, 0xffff0000, v90
	v_lshlrev_b32_e32 v142, 16, v91
	v_and_b32_e32 v143, 0xffff0000, v91
	v_lshlrev_b32_e32 v144, 16, v92
	v_and_b32_e32 v145, 0xffff0000, v92
	v_lshlrev_b32_e32 v146, 16, v93
	v_and_b32_e32 v147, 0xffff0000, v93
	v_lshlrev_b32_e32 v148, 16, v94
	v_and_b32_e32 v149, 0xffff0000, v94
	v_lshlrev_b32_e32 v150, 16, v95
	v_and_b32_e32 v151, 0xffff0000, v95
	s_lshl_b32 s100, s8, 13
	s_add_u32 s100, s100, 0x800
	s_mov_b32 s101, 0
	v_lshl_add_u64 v[164:165], v[4:5], 0, s[100:101]
	v_mul_f32_e32 v136, v136, v33
	v_mul_f32_e32 v137, v137, v33
	v_mul_f32_e32 v138, v138, v33
	v_mul_f32_e32 v139, v139, v33
	v_mul_f32_e32 v136, v64, v136
	v_mul_f32_e32 v137, v65, v137
	v_mul_f32_e32 v138, v66, v138
	v_mul_f32_e32 v139, v67, v139
	v_fma_f32 v136, v104, v136, v120
	v_fma_f32 v137, v105, v137, v121
	v_fma_f32 v138, v106, v138, v122
	v_fma_f32 v139, v107, v139, v123
	v_cvt_pk_bf16_f32 v166, v136, v137
	v_cvt_pk_bf16_f32 v167, v138, v139
	global_store_dwordx2 v[164:165], v[166:167], off offset:0
	v_mul_f32_e32 v140, v140, v33
	v_mul_f32_e32 v141, v141, v33
	v_mul_f32_e32 v142, v142, v33
	v_mul_f32_e32 v143, v143, v33
	v_mul_f32_e32 v140, v68, v140
	v_mul_f32_e32 v141, v69, v141
	v_mul_f32_e32 v142, v70, v142
	v_mul_f32_e32 v143, v71, v143
	v_fma_f32 v140, v108, v140, v124
	v_fma_f32 v141, v109, v141, v125
; __device__ __forceinline__ unsigned cvt_pk_bf16(float lo, float hi) { unsigned r; asm volatile("v_cvt_pk_bf16_f32 %0, %1, %2" : "=v"(r) : "v"(lo), "v"(hi)); return r; }
;     ...
;     if (F.gw >= wave0) for (int row = row_begin + (F.gw - wave0); row < nrows; row += F.NGW - wave0) {
;     ...
;         for (int j = 0; j < 4; ++j) { const f32x4 y = v[j] * rstd * g4[64 * j] * (sc4[64 * j] + 1.0f) + sh4[64 * j];
;             u32x2 w; w.x = cvt_pk_bf16(y.x, y.y); w.y = cvt_pk_bf16(y.z, y.w); o8[64 * j] = w; }
	v_fma_f32 v142, v110, v142, v126
	v_fma_f32 v143, v111, v143, v127
	v_cvt_pk_bf16_f32 v166, v140, v141
	v_cvt_pk_bf16_f32 v167, v142, v143
	global_store_dwordx2 v[164:165], v[166:167], off offset:512
	v_mul_f32_e32 v144, v144, v33
	v_mul_f32_e32 v145, v145, v33
	v_mul_f32_e32 v146, v146, v33
	v_mul_f32_e32 v147, v147, v33
	v_mul_f32_e32 v144, v72, v144
	v_mul_f32_e32 v145, v73, v145
	v_mul_f32_e32 v146, v74, v146
	v_mul_f32_e32 v147, v75, v147
	v_fma_f32 v144, v112, v144, v128
	v_fma_f32 v145, v113, v145, v129
	v_fma_f32 v146, v114, v146, v130
	v_fma_f32 v147, v115, v147, v131
	v_cvt_pk_bf16_f32 v166, v144, v145
	v_cvt_pk_bf16_f32 v167, v146, v147
	global_store_dwordx2 v[164:165], v[166:167], off offset:1024
	v_mul_f32_e32 v148, v148, v33
	v_mul_f32_e32 v149, v149, v33
	v_mul_f32_e32 v150, v150, v33
	v_mul_f32_e32 v151, v151, v33
	v_mul_f32_e32 v148, v76, v148
	v_mul_f32_e32 v149, v77, v149
	v_mul_f32_e32 v150, v78, v150
	v_mul_f32_e32 v151, v79, v151
	v_fma_f32 v148, v116, v148, v132
	v_fma_f32 v149, v117, v149, v133
	v_fma_f32 v150, v118, v150, v134
	v_fma_f32 v151, v119, v151, v135
	v_cvt_pk_bf16_f32 v166, v148, v149
	v_cvt_pk_bf16_f32 v167, v150, v151
	global_store_dwordx2 v[164:165], v[166:167], off offset:1536
	v_mov_b32_e32 v34, vcc_lo
	v_fmamk_f32 v34, v34, 0x3a800000, v14
	v_rsq_f32_e32 v33, v34
	v_lshlrev_b32_e32 v136, 16, v96
	v_and_b32_e32 v137, 0xffff0000, v96
	v_lshlrev_b32_e32 v138, 16, v97
	v_and_b32_e32 v139, 0xffff0000, v97
	v_lshlrev_b32_e32 v140, 16, v98
	v_and_b32_e32 v141, 0xffff0000, v98
	v_lshlrev_b32_e32 v142, 16, v99
	v_and_b32_e32 v143, 0xffff0000, v99
	v_lshlrev_b32_e32 v144, 16, v100
	v_and_b32_e32 v145, 0xffff0000, v100
	v_lshlrev_b32_e32 v146, 16, v101
	v_and_b32_e32 v147, 0xffff0000, v101
	v_lshlrev_b32_e32 v148, 16, v102
	v_and_b32_e32 v149, 0xffff0000, v102
	v_lshlrev_b32_e32 v150, 16, v103
	v_and_b32_e32 v151, 0xffff0000, v103
	s_lshl_b32 s100, s8, 13
	s_add_u32 s100, s100, 0x1000
	s_mov_b32 s101, 0
	v_lshl_add_u64 v[164:165], v[4:5], 0, s[100:101]
	v_mul_f32_e32 v136, v136, v33
	v_mul_f32_e32 v137, v137, v33
	v_mul_f32_e32 v138, v138, v33
	v_mul_f32_e32 v139, v139, v33
	v_mul_f32_e32 v136, v64, v136
	v_mul_f32_e32 v137, v65, v137
	v_mul_f32_e32 v138, v66, v138
	v_mul_f32_e32 v139, v67, v139
	v_fma_f32 v136, v104, v136, v120
	v_fma_f32 v137, v105, v137, v121
	v_fma_f32 v138, v106, v138, v122
	v_fma_f32 v139, v107, v139, v123
	v_cvt_pk_bf16_f32 v166, v136, v137
	v_cvt_pk_bf16_f32 v167, v138, v139
	global_store_dwordx2 v[164:165], v[166:167], off offset:0
	v_mul_f32_e32 v140, v140, v33
	v_mul_f32_e32 v141, v141, v33
	v_mul_f32_e32 v142, v142, v33
	v_mul_f32_e32 v143, v143, v33
	v_mul_f32_e32 v140, v68, v140
	v_mul_f32_e32 v141, v69, v141
	v_mul_f32_e32 v142, v70, v142
	v_mul_f32_e32 v143, v71, v143
	v_fma_f32 v140, v108, v140, v124
	v_fma_f32 v141, v109, v141, v125
	v_fma_f32 v142, v110, v142, v126
	v_fma_f32 v143, v111, v143, v127
	v_cvt_pk_bf16_f32 v166, v140, v141
	v_cvt_pk_bf16_f32 v167, v142, v143
	global_store_dwordx2 v[164:165], v[166:167], off offset:512
	v_mul_f32_e32 v144, v144, v33
	v_mul_f32_e32 v145, v145, v33
	v_mul_f32_e32 v146, v146, v33
	v_mul_f32_e32 v147, v147, v33
	v_mul_f32_e32 v144, v72, v144
	v_mul_f32_e32 v145, v73, v145
	v_mul_f32_e32 v146, v74, v146
	v_mul_f32_e32 v147, v75, v147
	v_fma_f32 v144, v112, v144, v128
	v_fma_f32 v145, v113, v145, v129
	v_fma_f32 v146, v114, v146, v130
	v_fma_f32 v147, v115, v147, v131
	v_cvt_pk_bf16_f32 v166, v144, v145
	v_cvt_pk_bf16_f32 v167, v146, v147
	global_store_dwordx2 v[164:165], v[166:167], off offset:1024
	v_mul_f32_e32 v148, v148, v33
	v_mul_f32_e32 v149, v149, v33
	v_mul_f32_e32 v150, v150, v33
	v_mul_f32_e32 v151, v151, v33
	v_mul_f32_e32 v148, v76, v148
	v_mul_f32_e32 v149, v77, v149
	v_mul_f32_e32 v150, v78, v150
	v_mul_f32_e32 v151, v79, v151
	v_fma_f32 v148, v116, v148, v132
	v_fma_f32 v149, v117, v149, v133
	v_fma_f32 v150, v118, v150, v134
	v_fma_f32 v151, v119, v151, v135
	v_cvt_pk_bf16_f32 v166, v148, v149
	v_cvt_pk_bf16_f32 v167, v150, v151
	global_store_dwordx2 v[164:165], v[166:167], off offset:1536
	v_mov_b32_e32 v34, vcc_hi
	v_fmamk_f32 v34, v34, 0x3a800000, v14
	v_rsq_f32_e32 v33, v34
	v_lshlrev_b32_e32 v136, 16, v156
	v_and_b32_e32 v137, 0xffff0000, v156
	v_lshlrev_b32_e32 v138, 16, v157
	v_and_b32_e32 v139, 0xffff0000, v157
	v_lshlrev_b32_e32 v140, 16, v158
	v_and_b32_e32 v141, 0xffff0000, v158
	v_lshlrev_b32_e32 v142, 16, v159
	v_and_b32_e32 v143, 0xffff0000, v159
	v_lshlrev_b32_e32 v144, 16, v160
	v_and_b32_e32 v145, 0xffff0000, v160
	v_lshlrev_b32_e32 v146, 16, v161
	v_and_b32_e32 v147, 0xffff0000, v161
	v_lshlrev_b32_e32 v148, 16, v162
	v_and_b32_e32 v149, 0xffff0000, v162
	v_lshlrev_b32_e32 v150, 16, v163
	v_and_b32_e32 v151, 0xffff0000, v163
	s_lshl_b32 s100, s8, 13
	s_add_u32 s100, s100, 0x1800
	s_mov_b32 s101, 0
	v_lshl_add_u64 v[164:165], v[4:5], 0, s[100:101]
	v_mul_f32_e32 v136, v136, v33
	v_mul_f32_e32 v137, v137, v33
	v_mul_f32_e32 v138, v138, v33
	v_mul_f32_e32 v139, v139, v33
	v_mul_f32_e32 v136, v64, v136
	v_mul_f32_e32 v137, v65, v137
	v_mul_f32_e32 v138, v66, v138
	v_mul_f32_e32 v139, v67, v139
	v_fma_f32 v136, v104, v136, v120
	v_fma_f32 v137, v105, v137, v121
	v_fma_f32 v138, v106, v138, v122
	v_fma_f32 v139, v107, v139, v123
	v_cvt_pk_bf16_f32 v166, v136, v137
	v_cvt_pk_bf16_f32 v167, v138, v139
	global_store_dwordx2 v[164:165], v[166:167], off offset:0
	v_mul_f32_e32 v140, v140, v33
	v_mul_f32_e32 v141, v141, v33
	v_mul_f32_e32 v142, v142, v33
	v_mul_f32_e32 v143, v143, v33
	v_mul_f32_e32 v140, v68, v140
	v_mul_f32_e32 v141, v69, v141
	v_mul_f32_e32 v142, v70, v142
	v_mul_f32_e32 v143, v71, v143
	v_fma_f32 v140, v108, v140, v124
	v_fma_f32 v141, v109, v141, v125
	v_fma_f32 v142, v110, v142, v126
	v_fma_f32 v143, v111, v143, v127
	v_cvt_pk_bf16_f32 v166, v140, v141
	v_cvt_pk_bf16_f32 v167, v142, v143
	global_store_dwordx2 v[164:165], v[166:167], off offset:512
	v_mul_f32_e32 v144, v144, v33
	v_mul_f32_e32 v145, v145, v33
	v_mul_f32_e32 v146, v146, v33
	v_mul_f32_e32 v147, v147, v33
	v_mul_f32_e32 v144, v72, v144
	v_mul_f32_e32 v145, v73, v145
	v_mul_f32_e32 v146, v74, v146
	v_mul_f32_e32 v147, v75, v147
	v_fma_f32 v144, v112, v144, v128
	v_fma_f32 v145, v113, v145, v129
	v_fma_f32 v146, v114, v146, v130
	v_fma_f32 v147, v115, v147, v131
	v_cvt_pk_bf16_f32 v166, v144, v145
	v_cvt_pk_bf16_f32 v167, v146, v147
	global_store_dwordx2 v[164:165], v[166:167], off offset:1024
	v_mul_f32_e32 v148, v148, v33
	v_mul_f32_e32 v149, v149, v33
	v_mul_f32_e32 v150, v150, v33
	v_mul_f32_e32 v151, v151, v33
	v_mul_f32_e32 v148, v76, v148
	v_mul_f32_e32 v149, v77, v149
	v_mul_f32_e32 v150, v78, v150
	v_mul_f32_e32 v151, v79, v151
	v_fma_f32 v148, v116, v148, v132
	v_fma_f32 v149, v117, v149, v133
	v_fma_f32 v150, v118, v150, v134
	v_fma_f32 v151, v119, v151, v135
	v_cvt_pk_bf16_f32 v166, v148, v149
	v_cvt_pk_bf16_f32 v167, v150, v151
	global_store_dwordx2 v[164:165], v[166:167], off offset:1536
	s_add_i32 s8, s8, s5
	s_lshl_b32 s9, s8, 2
	s_cmp_lt_i32 s9, 0x8000
	s_cbranch_scc1 .Lmn4_p11_blk

; __device__ __forceinline__ const float* inp(int k) { const CAS cfptr* p = (const CAS cfptr*)__builtin_amdgcn_kernarg_segment_ptr(); asm volatile("" : "+s"(p)); return p[k]; }
; #define LANE_IDS() const int f_tid = tid_(); const int f_lane = f_tid & 63; const int f_gtid = blockIdx.x * (NWAVES * 64) + f_tid; (void)f_lane; (void)f_gtid
; #define IN(k) ((((PH_MASK) >> (k)) & 1u) && kargs()->ph_lo <= (k) && (k) < kargs()->ph_hi)
;     LANE_IDS();
;     if (F.gw >= wave0) for (int row = row_begin + (F.gw - wave0); row < nrows; row += F.NGW - wave0) {
;         const bool isctx = row >= NLAT; const int b = isctx ? 8 : (row >> 12);
;         const size_t roff = isctx ? (size_t)(row - NLAT) * DM : (size_t)row * DM; const void* sp = isctx ? src_ctx : src_lat;
;         f32x4 v[4]; float ss = 0.f;
;         if (SB) { const u32x2* xr = (const u32x2*)((const bf16*)sp + roff) + f_lane;
; #pragma unroll
;             for (int j = 0; j < 4; ++j) { const u32x2 r = xr[64 * j]; v[j] = (f32x4){__uint_as_float(r.x << 16), __uint_as_float(r.x & 0xffff0000u), __uint_as_float(r.y << 16), __uint_as_float(r.y & 0xffff0000u)}; } }
;         else { const f32x4* xr = (const f32x4*)((const float*)sp + roff) + f_lane;
; #pragma unroll
;             for (int j = 0; j < 4; ++j) v[j] = xr[64 * j]; }
;         if (part != nullptr && isctx) {
;             const f32x4* p0 = (const f32x4*)(part + (size_t)(row - NLAT) * DM) + f_lane; const f32x4* p1 = p0 + (size_t)NCTX * DM / 4; const f32x4* g4p = (const f32x4*)pgate + f_lane;
; #pragma unroll
;             for (int j = 0; j < 4; ++j) v[j] += g4p[64 * j] * (p0[64 * j] + p1[64 * j]); }
; #pragma unroll
;         for (int j = 0; j < 4; ++j) ss += (v[j].x * v[j].x + v[j].y * v[j].y) + (v[j].z * v[j].z + v[j].w * v[j].w);
;         const float rstd = rsqrtf(wave_sum(ss) * (1.0f / DM) + EPS);
;         const f32x4* g4 = (const f32x4*)gnorm + f_lane; const f32x4* sh4 = (const f32x4*)(modl + b * MODS + shc * DM) + f_lane; const f32x4* sc4 = (const f32x4*)(modl + b * MODS + scc * DM) + f_lane;
; __global__ void __launch_bounds__(NWAVES * 64, 2) mk_fwd(Args args) {
;     ...
;     if (IN(18)) for (int rep_ = 0; rep_ < PH_REPS(18); ++rep_) { PH_PTRS(); modnorm_rows<true>(F, X + (size_t)NTOK * DM, X + (size_t)NTOK * DM, NLAT, H, inp(7) + DM, mod1, 3, 4); if (rep_ == PH_REPS(18) - 1) SEAM(18); }
.LBB0_1741:
	s_mov_b64 s[4:5], s[0:1]
	s_load_dword s3, s[4:5], 0xf8
	s_waitcnt lgkmcnt(0)
	s_cmp_gt_i32 s3, 18
	s_cbranch_scc1 .LBB0_1801
	s_mov_b64 s[4:5], s[0:1]
	s_load_dword s3, s[4:5], 0xfc
	s_waitcnt lgkmcnt(0)
	s_cmp_lt_i32 s3, 19
	s_cbranch_scc1 .LBB0_1801
	s_mov_b64 s[4:5], s[0:1]
	s_mov_b64 s[6:7], s[0:1]
	s_cmpk_gt_u32 s46, 0x7fff
	s_mov_b64 s[6:7], s[0:1]
	v_mov_b32_e32 v0, v188
	s_cbranch_scc1 .LBB0_1746
	v_and_b32_e32 v16, 63, v0
	v_mbcnt_lo_u32_b32 v0, -1, 0
	v_mbcnt_hi_u32_b32 v0, -1, v0
	v_and_b32_e32 v2, 64, v0
	v_add_u32_e32 v2, 64, v2
	v_xor_b32_e32 v3, 1, v0
	v_cmp_lt_i32_e32 vcc, v3, v2
	s_load_dwordx2 s[8:9], s[4:5], 0xf0
	s_load_dwordx2 s[12:13], s[6:7], 0x38
	v_cndmask_b32_e32 v3, v0, v3, vcc
	v_lshlrev_b32_e32 v8, 2, v3
	v_xor_b32_e32 v3, 2, v0
	v_cmp_lt_i32_e32 vcc, v3, v2
	v_mov_b32_e32 v1, 0
	s_mov_b64 s[4:5], 0x1000
	v_cndmask_b32_e32 v3, v0, v3, vcc
	v_lshlrev_b32_e32 v9, 2, v3
	v_xor_b32_e32 v3, 4, v0
	v_cmp_lt_i32_e32 vcc, v3, v2
	s_waitcnt lgkmcnt(0)
	s_add_u32 s3, s8, 0x37000
	s_addc_u32 s10, s9, 0
	v_cndmask_b32_e32 v3, v0, v3, vcc
	v_lshlrev_b32_e32 v10, 2, v3
	v_xor_b32_e32 v3, 8, v0
	v_cmp_lt_i32_e32 vcc, v3, v2
	v_mov_b32_e32 v14, 0x358637bd
	s_mov_b32 s11, 0x800000
	v_cndmask_b32_e32 v3, v0, v3, vcc
	v_lshlrev_b32_e32 v11, 2, v3
	v_xor_b32_e32 v3, 16, v0
	v_cmp_lt_i32_e32 vcc, v3, v2
	s_mov_b64 s[6:7], 0x4000
	s_nop 0
	v_cndmask_b32_e32 v3, v0, v3, vcc
	v_lshlrev_b32_e32 v12, 2, v3
	v_xor_b32_e32 v3, 32, v0
	v_cmp_lt_i32_e32 vcc, v3, v2
	s_nop 1
	v_cndmask_b32_e32 v0, v0, v3, vcc
	v_lshlrev_b32_e32 v13, 2, v0
	v_lshlrev_b32_e32 v0, 4, v16
	v_lshl_add_u64 v[2:3], s[12:13], 0, v[0:1]
	v_lshlrev_b32_e32 v0, 3, v16
	v_lshl_add_u64 v[2:3], v[2:3], 0, s[4:5]
	v_lshl_add_u64 v[6:7], s[8:9], 0, v[0:1]
	s_mov_b64 s[4:5], 0xe800000
	v_lshl_add_u64 v[4:5], v[6:7], 0, s[4:5]
	s_mov_b64 s[4:5], 0xa400000
	v_lshl_add_u64 v[6:7], v[6:7], 0, s[4:5]
	v_lshlrev_b32_e32 v0, 4, v16
	s_mov_b64 s[4:5], 0x3000
	s_movk_i32 s12, 0x4000
	s_movk_i32 s13, 0x3000
	global_load_dwordx4 v[64:67], v[2:3], off offset:0
	global_load_dwordx4 v[68:71], v[2:3], off offset:1024
	global_load_dwordx4 v[72:75], v[2:3], off offset:2048
	global_load_dwordx4 v[76:79], v[2:3], off offset:3072
	s_mov_b32 s8, s46
	s_lshl_b32 s9, s8, 2
	s_cmp_lt_i32 s9, 0x8000
	s_cbranch_scc0 .Lmn4_p18_done
.Lmn4_p18_blk:
	s_ashr_i32 s100, s8, 10
	s_mul_i32 s100, s100, 0x6000
	s_add_u32 s100, s3, s100
	s_addc_u32 s101, s10, 0
	s_add_u32 s14, s100, 0x4000
	s_addc_u32 s15, s101, 0
	v_lshl_add_u64 v[136:137], s[14:15], 0, v[0:1]
	global_load_dwordx4 v[104:107], v[136:137], off offset:0
	global_load_dwordx4 v[108:111], v[136:137], off offset:1024
	global_load_dwordx4 v[112:115], v[136:137], off offset:2048
	global_load_dwordx4 v[116:119], v[136:137], off offset:3072
	s_add_u32 s14, s100, 0x3000
	s_addc_u32 s15, s101, 0
	v_lshl_add_u64 v[138:139], s[14:15], 0, v[0:1]
	global_load_dwordx4 v[120:123], v[138:139], off offset:0
	global_load_dwordx4 v[124:127], v[138:139], off offset:1024
	global_load_dwordx4 v[128:131], v[138:139], off offset:2048
	global_load_dwordx4 v[132:135], v[138:139], off offset:3072
	s_lshl_b32 s100, s8, 13
	s_mov_b32 s101, 0
	v_lshl_add_u64 v[164:165], v[6:7], 0, s[100:101]
	global_load_dwordx2 v[80:81], v[164:165], off offset:0
	global_load_dwordx2 v[82:83], v[164:165], off offset:512
	global_load_dwordx2 v[84:85], v[164:165], off offset:1024
	global_load_dwordx2 v[86:87], v[164:165], off offset:1536
	s_lshl_b32 s100, s8, 13
	s_add_u32 s100, s100, 0x800
	s_mov_b32 s101, 0
	v_lshl_add_u64 v[164:165], v[6:7], 0, s[100:101]
	global_load_dwordx2 v[88:89], v[164:165], off offset:0
	global_load_dwordx2 v[90:91], v[164:165], off offset:512
	global_load_dwordx2 v[92:93], v[164:165], off offset:1024
	global_load_dwordx2 v[94:95], v[164:165], off offset:1536
	s_lshl_b32 s100, s8, 13
	s_add_u32 s100, s100, 0x1000
	s_mov_b32 s101, 0
	v_lshl_add_u64 v[164:165], v[6:7], 0, s[100:101]
	global_load_dwordx2 v[96:97], v[164:165], off offset:0
	global_load_dwordx2 v[98:99], v[164:165], off offset:512
	global_load_dwordx2 v[100:101], v[164:165], off offset:1024
	global_load_dwordx2 v[102:103], v[164:165], off offset:1536
	s_lshl_b32 s100, s8, 13
	s_add_u32 s100, s100, 0x1800
	s_mov_b32 s101, 0
	v_lshl_add_u64 v[164:165], v[6:7], 0, s[100:101]
	global_load_dwordx2 v[156:157], v[164:165], off offset:0
	global_load_dwordx2 v[158:159], v[164:165], off offset:512
	global_load_dwordx2 v[160:161], v[164:165], off offset:1024
	global_load_dwordx2 v[162:163], v[164:165], off offset:1536
	s_waitcnt vmcnt(0)
;     ...
;         if (SB) { const u32x2* xr = (const u32x2*)((const bf16*)sp + roff) + f_lane;
; #pragma unroll
;             for (int j = 0; j < 4; ++j) { const u32x2 r = xr[64 * j]; v[j] = (f32x4){__uint_as_float(r.x << 16), __uint_as_float(r.x & 0xffff0000u), __uint_as_float(r.y << 16), __uint_as_float(r.y & 0xffff0000u)}; } }
;         else { const f32x4* xr = (const f32x4*)((const float*)sp + roff) + f_lane;
; #pragma unroll
;             for (int j = 0; j < 4; ++j) v[j] = xr[64 * j]; }
;         if (part != nullptr && isctx) {
;             const f32x4* p0 = (const f32x4*)(part + (size_t)(row - NLAT) * DM) + f_lane; const f32x4* p1 = p0 + (size_t)NCTX * DM / 4; const f32x4* g4p = (const f32x4*)pgate + f_lane;
; #pragma unroll
;             for (int j = 0; j < 4; ++j) v[j] += g4p[64 * j] * (p0[64 * j] + p1[64 * j]); }
; #pragma unroll
;         for (int j = 0; j < 4; ++j) ss += (v[j].x * v[j].x + v[j].y * v[j].y) + (v[j].z * v[j].z + v[j].w * v[j].w);
;         const float rstd = rsqrtf(wave_sum(ss) * (1.0f / DM) + EPS);
	v_add_f32_e32 v104, 1.0, v104
	v_add_f32_e32 v105, 1.0, v105
	v_add_f32_e32 v106, 1.0, v106
	v_add_f32_e32 v107, 1.0, v107
	v_add_f32_e32 v108, 1.0, v108
	v_add_f32_e32 v109, 1.0, v109
	v_add_f32_e32 v110, 1.0, v110
	v_add_f32_e32 v111, 1.0, v111
	v_add_f32_e32 v112, 1.0, v112
	v_add_f32_e32 v113, 1.0, v113
	v_add_f32_e32 v114, 1.0, v114
	v_add_f32_e32 v115, 1.0, v115
	v_add_f32_e32 v116, 1.0, v116
	v_add_f32_e32 v117, 1.0, v117
	v_add_f32_e32 v118, 1.0, v118
	v_add_f32_e32 v119, 1.0, v119
	v_lshlrev_b32_e32 v136, 16, v80
	v_and_b32_e32 v137, 0xffff0000, v80
	v_lshlrev_b32_e32 v138, 16, v81
	v_and_b32_e32 v139, 0xffff0000, v81
	v_lshlrev_b32_e32 v140, 16, v82
	v_and_b32_e32 v141, 0xffff0000, v82
	v_lshlrev_b32_e32 v142, 16, v83
	v_and_b32_e32 v143, 0xffff0000, v83
	v_lshlrev_b32_e32 v144, 16, v84
	v_and_b32_e32 v145, 0xffff0000, v84
	v_lshlrev_b32_e32 v146, 16, v85
	v_and_b32_e32 v147, 0xffff0000, v85
	v_lshlrev_b32_e32 v148, 16, v86
	v_and_b32_e32 v149, 0xffff0000, v86
	v_lshlrev_b32_e32 v150, 16, v87
	v_and_b32_e32 v151, 0xffff0000, v87
	v_mul_f32_e32 v28, v136, v136
	v_mul_f32_e32 v32, v137, v137
	v_fmac_f32_e32 v28, v138, v138
	v_fmac_f32_e32 v32, v139, v139
	v_fmac_f32_e32 v28, v140, v140
	v_fmac_f32_e32 v32, v141, v141
	v_fmac_f32_e32 v28, v142, v142
	v_fmac_f32_e32 v32, v143, v143
	v_fmac_f32_e32 v28, v144, v144
	v_fmac_f32_e32 v32, v145, v145
	v_fmac_f32_e32 v28, v146, v146
	v_fmac_f32_e32 v32, v147, v147
	v_fmac_f32_e32 v28, v148, v148
	v_fmac_f32_e32 v32, v149, v149
	v_fmac_f32_e32 v28, v150, v150
	v_fmac_f32_e32 v32, v151, v151
	v_add_f32_e32 v28, v28, v32
	v_lshlrev_b32_e32 v136, 16, v88
	v_and_b32_e32 v137, 0xffff0000, v88
	v_lshlrev_b32_e32 v138, 16, v89
	v_and_b32_e32 v139, 0xffff0000, v89
	v_lshlrev_b32_e32 v140, 16, v90
	v_and_b32_e32 v141, 0xffff0000, v90
	v_lshlrev_b32_e32 v142, 16, v91
	v_and_b32_e32 v143, 0xffff0000, v91
	v_lshlrev_b32_e32 v144, 16, v92
	v_and_b32_e32 v145, 0xffff0000, v92
	v_lshlrev_b32_e32 v146, 16, v93
	v_and_b32_e32 v147, 0xffff0000, v93
	v_lshlrev_b32_e32 v148, 16, v94
	v_and_b32_e32 v149, 0xffff0000, v94
	v_lshlrev_b32_e32 v150, 16, v95
	v_and_b32_e32 v151, 0xffff0000, v95
	v_mul_f32_e32 v29, v136, v136
	v_mul_f32_e32 v32, v137, v137
	v_fmac_f32_e32 v29, v138, v138
	v_fmac_f32_e32 v32, v139, v139
	v_fmac_f32_e32 v29, v140, v140
	v_fmac_f32_e32 v32, v141, v141
	v_fmac_f32_e32 v29, v142, v142
	v_fmac_f32_e32 v32, v143, v143
	v_fmac_f32_e32 v29, v144, v144
	v_fmac_f32_e32 v32, v145, v145
	v_fmac_f32_e32 v29, v146, v146
	v_fmac_f32_e32 v32, v147, v147
	v_fmac_f32_e32 v29, v148, v148
	v_fmac_f32_e32 v32, v149, v149
	v_fmac_f32_e32 v29, v150, v150
	v_fmac_f32_e32 v32, v151, v151
	v_add_f32_e32 v29, v29, v32
	v_lshlrev_b32_e32 v136, 16, v96
	v_and_b32_e32 v137, 0xffff0000, v96
	v_lshlrev_b32_e32 v138, 16, v97
	v_and_b32_e32 v139, 0xffff0000, v97
	v_lshlrev_b32_e32 v140, 16, v98
	v_and_b32_e32 v141, 0xffff0000, v98
	v_lshlrev_b32_e32 v142, 16, v99
	v_and_b32_e32 v143, 0xffff0000, v99
	v_lshlrev_b32_e32 v144, 16, v100
	v_and_b32_e32 v145, 0xffff0000, v100
	v_lshlrev_b32_e32 v146, 16, v101
	v_and_b32_e32 v147, 0xffff0000, v101
	v_lshlrev_b32_e32 v148, 16, v102
	v_and_b32_e32 v149, 0xffff0000, v102
	v_lshlrev_b32_e32 v150, 16, v103
	v_and_b32_e32 v151, 0xffff0000, v103
	v_mul_f32_e32 v30, v136, v136
	v_mul_f32_e32 v32, v137, v137
	v_fmac_f32_e32 v30, v138, v138
	v_fmac_f32_e32 v32, v139, v139
	v_fmac_f32_e32 v30, v140, v140
	v_fmac_f32_e32 v32, v141, v141
	v_fmac_f32_e32 v30, v142, v142
	v_fmac_f32_e32 v32, v143, v143
	v_fmac_f32_e32 v30, v144, v144
	v_fmac_f32_e32 v32, v145, v145
	v_fmac_f32_e32 v30, v146, v146
	v_fmac_f32_e32 v32, v147, v147
	v_fmac_f32_e32 v30, v148, v148
	v_fmac_f32_e32 v32, v149, v149
	v_fmac_f32_e32 v30, v150, v150
	v_fmac_f32_e32 v32, v151, v151
	v_add_f32_e32 v30, v30, v32
	v_lshlrev_b32_e32 v136, 16, v156
	v_and_b32_e32 v137, 0xffff0000, v156
	v_lshlrev_b32_e32 v138, 16, v157
	v_and_b32_e32 v139, 0xffff0000, v157
	v_lshlrev_b32_e32 v140, 16, v158
	v_and_b32_e32 v141, 0xffff0000, v158
	v_lshlrev_b32_e32 v142, 16, v159
	v_and_b32_e32 v143, 0xffff0000, v159
	v_lshlrev_b32_e32 v144, 16, v160
	v_and_b32_e32 v145, 0xffff0000, v160
	v_lshlrev_b32_e32 v146, 16, v161
	v_and_b32_e32 v147, 0xffff0000, v161
	v_lshlrev_b32_e32 v148, 16, v162
	v_and_b32_e32 v149, 0xffff0000, v162
	v_lshlrev_b32_e32 v150, 16, v163
	v_and_b32_e32 v151, 0xffff0000, v163
	v_mul_f32_e32 v31, v136, v136
	v_mul_f32_e32 v32, v137, v137
	v_fmac_f32_e32 v31, v138, v138
	v_fmac_f32_e32 v32, v139, v139
	v_fmac_f32_e32 v31, v140, v140
	v_fmac_f32_e32 v32, v141, v141
	v_fmac_f32_e32 v31, v142, v142
	v_fmac_f32_e32 v32, v143, v143
	v_fmac_f32_e32 v31, v144, v144
	v_fmac_f32_e32 v32, v145, v145
	v_fmac_f32_e32 v31, v146, v146
	v_fmac_f32_e32 v32, v147, v147
	v_fmac_f32_e32 v31, v148, v148
	v_fmac_f32_e32 v32, v149, v149
	v_fmac_f32_e32 v31, v150, v150
	v_fmac_f32_e32 v32, v151, v151
	v_add_f32_e32 v31, v31, v32
	v_add_f32_dpp v28, v28, v28 row_shr:1 row_mask:0xf bank_mask:0xf bound_ctrl:0
	v_add_f32_dpp v29, v29, v29 row_shr:1 row_mask:0xf bank_mask:0xf bound_ctrl:0
	v_add_f32_dpp v30, v30, v30 row_shr:1 row_mask:0xf bank_mask:0xf bound_ctrl:0
	v_add_f32_dpp v31, v31, v31 row_shr:1 row_mask:0xf bank_mask:0xf bound_ctrl:0
	v_add_f32_dpp v28, v28, v28 row_shr:2 row_mask:0xf bank_mask:0xf bound_ctrl:0
	v_add_f32_dpp v29, v29, v29 row_shr:2 row_mask:0xf bank_mask:0xf bound_ctrl:0
	v_add_f32_dpp v30, v30, v30 row_shr:2 row_mask:0xf bank_mask:0xf bound_ctrl:0
	v_add_f32_dpp v31, v31, v31 row_shr:2 row_mask:0xf bank_mask:0xf bound_ctrl:0
	v_add_f32_dpp v28, v28, v28 row_shr:4 row_mask:0xf bank_mask:0xf bound_ctrl:0
; __device__ __forceinline__ unsigned cvt_pk_bf16(float lo, float hi) { unsigned r; asm volatile("v_cvt_pk_bf16_f32 %0, %1, %2" : "=v"(r) : "v"(lo), "v"(hi)); return r; }
;     ...
;         const float rstd = rsqrtf(wave_sum(ss) * (1.0f / DM) + EPS);
;         const f32x4* g4 = (const f32x4*)gnorm + f_lane; const f32x4* sh4 = (const f32x4*)(modl + b * MODS + shc * DM) + f_lane; const f32x4* sc4 = (const f32x4*)(modl + b * MODS + scc * DM) + f_lane;
;         u32x2* o8 = (u32x2*)(H + (size_t)row * DM) + f_lane;
; #pragma unroll
;         for (int j = 0; j < 4; ++j) { const f32x4 y = v[j] * rstd * g4[64 * j] * (sc4[64 * j] + 1.0f) + sh4[64 * j];
;             u32x2 w; w.x = cvt_pk_bf16(y.x, y.y); w.y = cvt_pk_bf16(y.z, y.w); o8[64 * j] = w; }
	v_add_f32_dpp v29, v29, v29 row_shr:4 row_mask:0xf bank_mask:0xf bound_ctrl:0
	v_add_f32_dpp v30, v30, v30 row_shr:4 row_mask:0xf bank_mask:0xf bound_ctrl:0
	v_add_f32_dpp v31, v31, v31 row_shr:4 row_mask:0xf bank_mask:0xf bound_ctrl:0
	v_add_f32_dpp v28, v28, v28 row_shr:8 row_mask:0xf bank_mask:0xf bound_ctrl:0
	v_add_f32_dpp v29, v29, v29 row_shr:8 row_mask:0xf bank_mask:0xf bound_ctrl:0
	v_add_f32_dpp v30, v30, v30 row_shr:8 row_mask:0xf bank_mask:0xf bound_ctrl:0
	v_add_f32_dpp v31, v31, v31 row_shr:8 row_mask:0xf bank_mask:0xf bound_ctrl:0
	v_add_f32_dpp v28, v28, v28 row_bcast:15 row_mask:0xa bank_mask:0xf
	v_add_f32_dpp v29, v29, v29 row_bcast:15 row_mask:0xa bank_mask:0xf
	v_add_f32_dpp v30, v30, v30 row_bcast:15 row_mask:0xa bank_mask:0xf
	v_add_f32_dpp v31, v31, v31 row_bcast:15 row_mask:0xa bank_mask:0xf
	v_add_f32_dpp v28, v28, v28 row_bcast:31 row_mask:0xc bank_mask:0xf
	v_add_f32_dpp v29, v29, v29 row_bcast:31 row_mask:0xc bank_mask:0xf
	v_add_f32_dpp v30, v30, v30 row_bcast:31 row_mask:0xc bank_mask:0xf
	v_add_f32_dpp v31, v31, v31 row_bcast:31 row_mask:0xc bank_mask:0xf
	s_nop 0
	v_readlane_b32 s14, v28, 63
	v_readlane_b32 s15, v29, 63
	v_readlane_b32 vcc_lo, v30, 63
	v_readlane_b32 vcc_hi, v31, 63
	v_mov_b32_e32 v34, s14
	v_fmamk_f32 v34, v34, 0x3a800000, v14
	v_rsq_f32_e32 v33, v34
	v_lshlrev_b32_e32 v136, 16, v80
	v_and_b32_e32 v137, 0xffff0000, v80
	v_lshlrev_b32_e32 v138, 16, v81
	v_and_b32_e32 v139, 0xffff0000, v81
	v_lshlrev_b32_e32 v140, 16, v82
	v_and_b32_e32 v141, 0xffff0000, v82
	v_lshlrev_b32_e32 v142, 16, v83
	v_and_b32_e32 v143, 0xffff0000, v83
	v_lshlrev_b32_e32 v144, 16, v84
	v_and_b32_e32 v145, 0xffff0000, v84
	v_lshlrev_b32_e32 v146, 16, v85
	v_and_b32_e32 v147, 0xffff0000, v85
	v_lshlrev_b32_e32 v148, 16, v86
	v_and_b32_e32 v149, 0xffff0000, v86
	v_lshlrev_b32_e32 v150, 16, v87
	v_and_b32_e32 v151, 0xffff0000, v87
	s_lshl_b32 s100, s8, 13
	s_mov_b32 s101, 0
	v_lshl_add_u64 v[164:165], v[4:5], 0, s[100:101]
	v_mul_f32_e32 v136, v136, v33
	v_mul_f32_e32 v137, v137, v33
	v_mul_f32_e32 v138, v138, v33
	v_mul_f32_e32 v139, v139, v33
	v_mul_f32_e32 v136, v64, v136
	v_mul_f32_e32 v137, v65, v137
	v_mul_f32_e32 v138, v66, v138
	v_mul_f32_e32 v139, v67, v139
	v_fma_f32 v136, v104, v136, v120
	v_fma_f32 v137, v105, v137, v121
	v_fma_f32 v138, v106, v138, v122
	v_fma_f32 v139, v107, v139, v123
	v_cvt_pk_bf16_f32 v166, v136, v137
	v_cvt_pk_bf16_f32 v167, v138, v139
	global_store_dwordx2 v[164:165], v[166:167], off offset:0
	v_mul_f32_e32 v140, v140, v33
	v_mul_f32_e32 v141, v141, v33
	v_mul_f32_e32 v142, v142, v33
	v_mul_f32_e32 v143, v143, v33
	v_mul_f32_e32 v140, v68, v140
	v_mul_f32_e32 v141, v69, v141
	v_mul_f32_e32 v142, v70, v142
	v_mul_f32_e32 v143, v71, v143
	v_fma_f32 v140, v108, v140, v124
	v_fma_f32 v141, v109, v141, v125
	v_fma_f32 v142, v110, v142, v126
	v_fma_f32 v143, v111, v143, v127
	v_cvt_pk_bf16_f32 v166, v140, v141
	v_cvt_pk_bf16_f32 v167, v142, v143
	global_store_dwordx2 v[164:165], v[166:167], off offset:512
	v_mul_f32_e32 v144, v144, v33
	v_mul_f32_e32 v145, v145, v33
	v_mul_f32_e32 v146, v146, v33
	v_mul_f32_e32 v147, v147, v33
	v_mul_f32_e32 v144, v72, v144
	v_mul_f32_e32 v145, v73, v145
	v_mul_f32_e32 v146, v74, v146
	v_mul_f32_e32 v147, v75, v147
	v_fma_f32 v144, v112, v144, v128
	v_fma_f32 v145, v113, v145, v129
	v_fma_f32 v146, v114, v146, v130
	v_fma_f32 v147, v115, v147, v131
	v_cvt_pk_bf16_f32 v166, v144, v145
	v_cvt_pk_bf16_f32 v167, v146, v147
	global_store_dwordx2 v[164:165], v[166:167], off offset:1024
	v_mul_f32_e32 v148, v148, v33
	v_mul_f32_e32 v149, v149, v33
	v_mul_f32_e32 v150, v150, v33
	v_mul_f32_e32 v151, v151, v33
	v_mul_f32_e32 v148, v76, v148
	v_mul_f32_e32 v149, v77, v149
	v_mul_f32_e32 v150, v78, v150
	v_mul_f32_e32 v151, v79, v151
	v_fma_f32 v148, v116, v148, v132
	v_fma_f32 v149, v117, v149, v133
	v_fma_f32 v150, v118, v150, v134
	v_fma_f32 v151, v119, v151, v135
	v_cvt_pk_bf16_f32 v166, v148, v149
	v_cvt_pk_bf16_f32 v167, v150, v151
	global_store_dwordx2 v[164:165], v[166:167], off offset:1536
	v_mov_b32_e32 v34, s15
	v_fmamk_f32 v34, v34, 0x3a800000, v14
	v_rsq_f32_e32 v33, v34
	v_lshlrev_b32_e32 v136, 16, v88
	v_and_b32_e32 v137, 0xffff0000, v88
	v_lshlrev_b32_e32 v138, 16, v89
	v_and_b32_e32 v139, 0xffff0000, v89
	v_lshlrev_b32_e32 v140, 16, v90
	v_and_b32_e32 v141, 0xffff0000, v90
	v_lshlrev_b32_e32 v142, 16, v91
	v_and_b32_e32 v143, 0xffff0000, v91
	v_lshlrev_b32_e32 v144, 16, v92
	v_and_b32_e32 v145, 0xffff0000, v92
	v_lshlrev_b32_e32 v146, 16, v93
	v_and_b32_e32 v147, 0xffff0000, v93
	v_lshlrev_b32_e32 v148, 16, v94
	v_and_b32_e32 v149, 0xffff0000, v94
	v_lshlrev_b32_e32 v150, 16, v95
	v_and_b32_e32 v151, 0xffff0000, v95
	s_lshl_b32 s100, s8, 13
	s_add_u32 s100, s100, 0x800
	s_mov_b32 s101, 0
	v_lshl_add_u64 v[164:165], v[4:5], 0, s[100:101]
	v_mul_f32_e32 v136, v136, v33
	v_mul_f32_e32 v137, v137, v33
	v_mul_f32_e32 v138, v138, v33
	v_mul_f32_e32 v139, v139, v33
	v_mul_f32_e32 v136, v64, v136
	v_mul_f32_e32 v137, v65, v137
	v_mul_f32_e32 v138, v66, v138
	v_mul_f32_e32 v139, v67, v139
	v_fma_f32 v136, v104, v136, v120
	v_fma_f32 v137, v105, v137, v121
	v_fma_f32 v138, v106, v138, v122
	v_fma_f32 v139, v107, v139, v123
	v_cvt_pk_bf16_f32 v166, v136, v137
	v_cvt_pk_bf16_f32 v167, v138, v139
	global_store_dwordx2 v[164:165], v[166:167], off offset:0
	v_mul_f32_e32 v140, v140, v33
	v_mul_f32_e32 v141, v141, v33
	v_mul_f32_e32 v142, v142, v33
	v_mul_f32_e32 v143, v143, v33
	v_mul_f32_e32 v140, v68, v140
	v_mul_f32_e32 v141, v69, v141
	v_mul_f32_e32 v142, v70, v142
	v_mul_f32_e32 v143, v71, v143
	v_fma_f32 v140, v108, v140, v124
	v_fma_f32 v141, v109, v141, v125
; __device__ __forceinline__ unsigned cvt_pk_bf16(float lo, float hi) { unsigned r; asm volatile("v_cvt_pk_bf16_f32 %0, %1, %2" : "=v"(r) : "v"(lo), "v"(hi)); return r; }
;     ...
;     if (F.gw >= wave0) for (int row = row_begin + (F.gw - wave0); row < nrows; row += F.NGW - wave0) {
;     ...
;         for (int j = 0; j < 4; ++j) { const f32x4 y = v[j] * rstd * g4[64 * j] * (sc4[64 * j] + 1.0f) + sh4[64 * j];
;             u32x2 w; w.x = cvt_pk_bf16(y.x, y.y); w.y = cvt_pk_bf16(y.z, y.w); o8[64 * j] = w; }
	v_fma_f32 v142, v110, v142, v126
	v_fma_f32 v143, v111, v143, v127
	v_cvt_pk_bf16_f32 v166, v140, v141
	v_cvt_pk_bf16_f32 v167, v142, v143
	global_store_dwordx2 v[164:165], v[166:167], off offset:512
	v_mul_f32_e32 v144, v144, v33
	v_mul_f32_e32 v145, v145, v33
	v_mul_f32_e32 v146, v146, v33
	v_mul_f32_e32 v147, v147, v33
	v_mul_f32_e32 v144, v72, v144
	v_mul_f32_e32 v145, v73, v145
	v_mul_f32_e32 v146, v74, v146
	v_mul_f32_e32 v147, v75, v147
	v_fma_f32 v144, v112, v144, v128
	v_fma_f32 v145, v113, v145, v129
	v_fma_f32 v146, v114, v146, v130
	v_fma_f32 v147, v115, v147, v131
	v_cvt_pk_bf16_f32 v166, v144, v145
	v_cvt_pk_bf16_f32 v167, v146, v147
	global_store_dwordx2 v[164:165], v[166:167], off offset:1024
	v_mul_f32_e32 v148, v148, v33
	v_mul_f32_e32 v149, v149, v33
	v_mul_f32_e32 v150, v150, v33
	v_mul_f32_e32 v151, v151, v33
	v_mul_f32_e32 v148, v76, v148
	v_mul_f32_e32 v149, v77, v149
	v_mul_f32_e32 v150, v78, v150
	v_mul_f32_e32 v151, v79, v151
	v_fma_f32 v148, v116, v148, v132
	v_fma_f32 v149, v117, v149, v133
	v_fma_f32 v150, v118, v150, v134
	v_fma_f32 v151, v119, v151, v135
	v_cvt_pk_bf16_f32 v166, v148, v149
	v_cvt_pk_bf16_f32 v167, v150, v151
	global_store_dwordx2 v[164:165], v[166:167], off offset:1536
	v_mov_b32_e32 v34, vcc_lo
	v_fmamk_f32 v34, v34, 0x3a800000, v14
	v_rsq_f32_e32 v33, v34
	v_lshlrev_b32_e32 v136, 16, v96
	v_and_b32_e32 v137, 0xffff0000, v96
	v_lshlrev_b32_e32 v138, 16, v97
	v_and_b32_e32 v139, 0xffff0000, v97
	v_lshlrev_b32_e32 v140, 16, v98
	v_and_b32_e32 v141, 0xffff0000, v98
	v_lshlrev_b32_e32 v142, 16, v99
	v_and_b32_e32 v143, 0xffff0000, v99
	v_lshlrev_b32_e32 v144, 16, v100
	v_and_b32_e32 v145, 0xffff0000, v100
	v_lshlrev_b32_e32 v146, 16, v101
	v_and_b32_e32 v147, 0xffff0000, v101
	v_lshlrev_b32_e32 v148, 16, v102
	v_and_b32_e32 v149, 0xffff0000, v102
	v_lshlrev_b32_e32 v150, 16, v103
	v_and_b32_e32 v151, 0xffff0000, v103
	s_lshl_b32 s100, s8, 13
	s_add_u32 s100, s100, 0x1000
	s_mov_b32 s101, 0
	v_lshl_add_u64 v[164:165], v[4:5], 0, s[100:101]
	v_mul_f32_e32 v136, v136, v33
	v_mul_f32_e32 v137, v137, v33
	v_mul_f32_e32 v138, v138, v33
	v_mul_f32_e32 v139, v139, v33
	v_mul_f32_e32 v136, v64, v136
	v_mul_f32_e32 v137, v65, v137
	v_mul_f32_e32 v138, v66, v138
	v_mul_f32_e32 v139, v67, v139
	v_fma_f32 v136, v104, v136, v120
	v_fma_f32 v137, v105, v137, v121
	v_fma_f32 v138, v106, v138, v122
	v_fma_f32 v139, v107, v139, v123
	v_cvt_pk_bf16_f32 v166, v136, v137
	v_cvt_pk_bf16_f32 v167, v138, v139
	global_store_dwordx2 v[164:165], v[166:167], off offset:0
	v_mul_f32_e32 v140, v140, v33
	v_mul_f32_e32 v141, v141, v33
	v_mul_f32_e32 v142, v142, v33
	v_mul_f32_e32 v143, v143, v33
	v_mul_f32_e32 v140, v68, v140
	v_mul_f32_e32 v141, v69, v141
	v_mul_f32_e32 v142, v70, v142
	v_mul_f32_e32 v143, v71, v143
	v_fma_f32 v140, v108, v140, v124
	v_fma_f32 v141, v109, v141, v125
	v_fma_f32 v142, v110, v142, v126
	v_fma_f32 v143, v111, v143, v127
	v_cvt_pk_bf16_f32 v166, v140, v141
	v_cvt_pk_bf16_f32 v167, v142, v143
	global_store_dwordx2 v[164:165], v[166:167], off offset:512
	v_mul_f32_e32 v144, v144, v33
	v_mul_f32_e32 v145, v145, v33
	v_mul_f32_e32 v146, v146, v33
	v_mul_f32_e32 v147, v147, v33
	v_mul_f32_e32 v144, v72, v144
	v_mul_f32_e32 v145, v73, v145
	v_mul_f32_e32 v146, v74, v146
	v_mul_f32_e32 v147, v75, v147
	v_fma_f32 v144, v112, v144, v128
	v_fma_f32 v145, v113, v145, v129
	v_fma_f32 v146, v114, v146, v130
	v_fma_f32 v147, v115, v147, v131
	v_cvt_pk_bf16_f32 v166, v144, v145
	v_cvt_pk_bf16_f32 v167, v146, v147
	global_store_dwordx2 v[164:165], v[166:167], off offset:1024
	v_mul_f32_e32 v148, v148, v33
	v_mul_f32_e32 v149, v149, v33
	v_mul_f32_e32 v150, v150, v33
	v_mul_f32_e32 v151, v151, v33
	v_mul_f32_e32 v148, v76, v148
	v_mul_f32_e32 v149, v77, v149
	v_mul_f32_e32 v150, v78, v150
	v_mul_f32_e32 v151, v79, v151
	v_fma_f32 v148, v116, v148, v132
	v_fma_f32 v149, v117, v149, v133
	v_fma_f32 v150, v118, v150, v134
	v_fma_f32 v151, v119, v151, v135
	v_cvt_pk_bf16_f32 v166, v148, v149
	v_cvt_pk_bf16_f32 v167, v150, v151
	global_store_dwordx2 v[164:165], v[166:167], off offset:1536
	v_mov_b32_e32 v34, vcc_hi
	v_fmamk_f32 v34, v34, 0x3a800000, v14
	v_rsq_f32_e32 v33, v34
	v_lshlrev_b32_e32 v136, 16, v156
	v_and_b32_e32 v137, 0xffff0000, v156
	v_lshlrev_b32_e32 v138, 16, v157
	v_and_b32_e32 v139, 0xffff0000, v157
	v_lshlrev_b32_e32 v140, 16, v158
	v_and_b32_e32 v141, 0xffff0000, v158
	v_lshlrev_b32_e32 v142, 16, v159
	v_and_b32_e32 v143, 0xffff0000, v159
	v_lshlrev_b32_e32 v144, 16, v160
	v_and_b32_e32 v145, 0xffff0000, v160
	v_lshlrev_b32_e32 v146, 16, v161
	v_and_b32_e32 v147, 0xffff0000, v161
	v_lshlrev_b32_e32 v148, 16, v162
	v_and_b32_e32 v149, 0xffff0000, v162
	v_lshlrev_b32_e32 v150, 16, v163
	v_and_b32_e32 v151, 0xffff0000, v163
	s_lshl_b32 s100, s8, 13
	s_add_u32 s100, s100, 0x1800
	s_mov_b32 s101, 0
	v_lshl_add_u64 v[164:165], v[4:5], 0, s[100:101]
	v_mul_f32_e32 v136, v136, v33
	v_mul_f32_e32 v137, v137, v33
	v_mul_f32_e32 v138, v138, v33
	v_mul_f32_e32 v139, v139, v33
	v_mul_f32_e32 v136, v64, v136
	v_mul_f32_e32 v137, v65, v137
	v_mul_f32_e32 v138, v66, v138
	v_mul_f32_e32 v139, v67, v139
	v_fma_f32 v136, v104, v136, v120
	v_fma_f32 v137, v105, v137, v121
	v_fma_f32 v138, v106, v138, v122
	v_fma_f32 v139, v107, v139, v123
	v_cvt_pk_bf16_f32 v166, v136, v137
	v_cvt_pk_bf16_f32 v167, v138, v139
	global_store_dwordx2 v[164:165], v[166:167], off offset:0
	v_mul_f32_e32 v140, v140, v33
	v_mul_f32_e32 v141, v141, v33
	v_mul_f32_e32 v142, v142, v33
	v_mul_f32_e32 v143, v143, v33
	v_mul_f32_e32 v140, v68, v140
	v_mul_f32_e32 v141, v69, v141
	v_mul_f32_e32 v142, v70, v142
	v_mul_f32_e32 v143, v71, v143
	v_fma_f32 v140, v108, v140, v124
	v_fma_f32 v141, v109, v141, v125
	v_fma_f32 v142, v110, v142, v126
	v_fma_f32 v143, v111, v143, v127
	v_cvt_pk_bf16_f32 v166, v140, v141
	v_cvt_pk_bf16_f32 v167, v142, v143
	global_store_dwordx2 v[164:165], v[166:167], off offset:512
	v_mul_f32_e32 v144, v144, v33
	v_mul_f32_e32 v145, v145, v33
	v_mul_f32_e32 v146, v146, v33
	v_mul_f32_e32 v147, v147, v33
	v_mul_f32_e32 v144, v72, v144
	v_mul_f32_e32 v145, v73, v145
	v_mul_f32_e32 v146, v74, v146
	v_mul_f32_e32 v147, v75, v147
	v_fma_f32 v144, v112, v144, v128
	v_fma_f32 v145, v113, v145, v129
	v_fma_f32 v146, v114, v146, v130
	v_fma_f32 v147, v115, v147, v131
	v_cvt_pk_bf16_f32 v166, v144, v145
	v_cvt_pk_bf16_f32 v167, v146, v147
	global_store_dwordx2 v[164:165], v[166:167], off offset:1024
	v_mul_f32_e32 v148, v148, v33
	v_mul_f32_e32 v149, v149, v33
	v_mul_f32_e32 v150, v150, v33
	v_mul_f32_e32 v151, v151, v33
	v_mul_f32_e32 v148, v76, v148
	v_mul_f32_e32 v149, v77, v149
	v_mul_f32_e32 v150, v78, v150
	v_mul_f32_e32 v151, v79, v151
	v_fma_f32 v148, v116, v148, v132
	v_fma_f32 v149, v117, v149, v133
	v_fma_f32 v150, v118, v150, v134
	v_fma_f32 v151, v119, v151, v135
	v_cvt_pk_bf16_f32 v166, v148, v149
	v_cvt_pk_bf16_f32 v167, v150, v151
	global_store_dwordx2 v[164:165], v[166:167], off offset:1536
	s_add_i32 s8, s8, s76
	s_lshl_b32 s9, s8, 2
	s_cmp_lt_i32 s9, 0x8000
	s_cbranch_scc1 .Lmn4_p18_blk
;     ...
;     if (F.gw >= wave0) for (int row = row_begin + (F.gw - wave0); row < nrows; row += F.NGW - wave0) {
.Lmn4_p18_done:
.Lmn4_p18_fin:
	s_add_i32 s46, s46, s76
	s_cmp_lt_i32 s46, 0x8000
	s_cbranch_scc1 .Lmn4_p18_fin
